# GEMM load segments: LDS-DMA address computation placed behind the M0 write so it supplies the hazard wait state (40 s_nop 0 removed)
# speedup vs baseline: 1.0040x; 1.0007x over previous
; #define PG8_STAGE(bufoff, gbase, voff) do { _Pragma("unroll") for (int _i = 0; _i < 2; ++_i) \
;         __builtin_amdgcn_global_load_lds((const unsigned*)((const char*)(gbase) + (voff)[_i]), (PG8_LAS unsigned*)(lds + (bufoff) + ldsw + _i * 8192), 16, 0, 0); } while (0)
; #define PG8_LDA(dst, b, h) do { _Pragma("unroll") for (int m = 0; m < 4; ++m) _Pragma("unroll") for (int k = 0; k < 2; ++k) dst[m][k] = *(const PG8_LAS bf16x8*)(lds + PG8_SA(b, h) + aoff + m * 2048 + k * 1024); } while (0)
; #define PG8_LDB(dst, b, h) do { _Pragma("unroll") for (int n = 0; n < 2; ++n) _Pragma("unroll") for (int k = 0; k < 2; ++k) dst[n][k] = *(const PG8_LAS bf16x8*)(lds + PG8_SB(b, h) + boff + n * 2048 + k * 1024); } while (0)
; #define PG8_MMA(ai, bj, At, Bt) do { __builtin_amdgcn_s_setprio(1); _Pragma("unroll") for (int m = 0; m < 4; ++m) _Pragma("unroll") for (int n = 0; n < 2; ++n) _Pragma("unroll") for (int k = 0; k < 2; ++k) \
;         acc[ai][bj][m][n] = __builtin_amdgcn_mfma_f32_16x16x32_bf16(Bt[n][k], At[m][k], acc[ai][bj][m][n], 0, 0, 0); __builtin_amdgcn_s_setprio(0); } while (0)
; #define PG8_WAIT_V(n) asm volatile("s_waitcnt vmcnt(" #n ")" ::: "memory")
; #define PG8_WAIT_L(n) asm volatile("s_waitcnt lgkmcnt(" #n ")" ::: "memory")
; #define PG8_BAR __builtin_amdgcn_s_barrier()
; #define PG8_SCHED __builtin_amdgcn_sched_barrier(0)
; template <class Epi, class Sched, bool ALIGN_EPI = false, bool SP2 = false>
; __device__ __forceinline__ void gemm_phase(PG8_LAS unsigned char* lds, const Gemm g, const Sched& S, const Epi& E) {
;     ...
;         for (int t = 0; t < nt; t += 2) {
;             const bool last = (t == nt - 2);
;             const char* a1 = cA + (size_t)(t + 1) * kstep;
;             const char* a2 = last ? nA : cA + (size_t)(t + 2) * kstep; const char* b2 = last ? nB : cB + (size_t)(t + 2) * kstep;
;             const char* a3 = a2 + kstep; const char* b3 = b2 + kstep;
;             if (last && has_next) S.a_ready(nxt);
;             if constexpr (SP2) {
;             PG8_LDB(B0, 0, 0); PG8_LDB(B1, 0, 1); PG8_SCHED; PG8_LDA(At, 0, 0); PG8_STAGE(PG8_SA(1, 1), a1 + hstep, voffA);
;             PG8_WAIT_V(8); PG8_WAIT_L(0); PG8_BAR; PG8_MMA(0, 0, At, B0); PG8_MMA(0, 1, At, B1); PG8_BAR; PG8_SCHED;
;             PG8_LDA(At, 0, 1); PG8_STAGE(PG8_SB(0, 0), b2, voffB); PG8_STAGE(PG8_SB(0, 1), b2 + hstep, voffB); PG8_STAGE(PG8_SA(0, 0), a2, voffA);
.LBB0_71:
	s_add_u32 s18, s16, 0xfffc0080
	s_addc_u32 s19, s17, -1
	s_cmp_eq_u32 s38, 12
	s_cselect_b32 s21, s9, s19
	s_cselect_b32 s20, s34, s18
	s_cselect_b32 s19, s7, s37
	s_cselect_b32 s18, s35, s36
	s_add_i32 s39, 0, 0x10000
	s_add_i32 s44, 0, 0x14000
	v_add_u32_e32 v154, s39, v140
	v_add_u32_e32 v170, s44, v140
	ds_read_b128 v[142:145], v154
	ds_read_b128 v[146:149], v154 offset:1024
	ds_read_b128 v[150:153], v154 offset:2048
	ds_read_b128 v[154:157], v154 offset:3072
	ds_read_b128 v[158:161], v170
	ds_read_b128 v[162:165], v170 offset:1024
	ds_read_b128 v[166:169], v170 offset:2048
	ds_read_b128 v[170:173], v170 offset:3072
	v_lshl_add_u64 v[210:211], s[16:17], 0, v[136:137]
	s_add_i32 m0, s25, 0xc000
	ds_read_b128 v[174:177], v141
	ds_read_b128 v[178:181], v141 offset:1024
	ds_read_b128 v[182:185], v141 offset:2048
	ds_read_b128 v[186:189], v141 offset:3072
	ds_read_b128 v[190:193], v141 offset:4096
	ds_read_b128 v[194:197], v141 offset:5120
	ds_read_b128 v[198:201], v141 offset:6144
	ds_read_b128 v[206:209], v141 offset:7168
	global_load_lds_dwordx4 v[210:211], off
	s_add_i32 m0, s25, 0xe000
	v_lshl_add_u64 v[210:211], s[16:17], 0, v[138:139]
	global_load_lds_dwordx4 v[210:211], off
	s_waitcnt vmcnt(8)
	s_waitcnt lgkmcnt(0)
	s_barrier
	s_setprio 1
	s_waitcnt lgkmcnt(0)
	v_mfma_f32_16x16x32_bf16 v[126:129], v[142:145], v[174:177], v[126:129]
	v_mfma_f32_16x16x32_bf16 v[122:125], v[150:153], v[174:177], v[122:125]
	v_mfma_f32_16x16x32_bf16 v[110:113], v[142:145], v[182:185], v[110:113]
	v_mfma_f32_16x16x32_bf16 v[106:109], v[150:153], v[182:185], v[106:109]
	v_mfma_f32_16x16x32_bf16 v[94:97], v[142:145], v[190:193], v[94:97]
	v_mfma_f32_16x16x32_bf16 v[90:93], v[150:153], v[190:193], v[90:93]
	v_mfma_f32_16x16x32_bf16 v[78:81], v[142:145], v[198:201], v[78:81]
	v_mfma_f32_16x16x32_bf16 v[74:77], v[150:153], v[198:201], v[74:77]
	v_mfma_f32_16x16x32_bf16 v[126:129], v[146:149], v[178:181], v[126:129]
	v_mfma_f32_16x16x32_bf16 v[122:125], v[154:157], v[178:181], v[122:125]
	v_mfma_f32_16x16x32_bf16 v[110:113], v[146:149], v[186:189], v[110:113]
	v_mfma_f32_16x16x32_bf16 v[106:109], v[154:157], v[186:189], v[106:109]
	v_mfma_f32_16x16x32_bf16 v[94:97], v[146:149], v[194:197], v[94:97]
	v_mfma_f32_16x16x32_bf16 v[90:93], v[154:157], v[194:197], v[90:93]
	v_mfma_f32_16x16x32_bf16 v[78:81], v[146:149], v[206:209], v[78:81]
	v_mfma_f32_16x16x32_bf16 v[74:77], v[154:157], v[206:209], v[74:77]
	s_setprio 0
	s_setprio 1
	v_mfma_f32_16x16x32_bf16 v[118:121], v[158:161], v[174:177], v[118:121]
	v_mfma_f32_16x16x32_bf16 v[114:117], v[166:169], v[174:177], v[114:117]
	v_mfma_f32_16x16x32_bf16 v[102:105], v[158:161], v[182:185], v[102:105]
	v_mfma_f32_16x16x32_bf16 v[98:101], v[166:169], v[182:185], v[98:101]
	v_mfma_f32_16x16x32_bf16 v[86:89], v[158:161], v[190:193], v[86:89]
	v_mfma_f32_16x16x32_bf16 v[82:85], v[166:169], v[190:193], v[82:85]
	v_mfma_f32_16x16x32_bf16 v[70:73], v[158:161], v[198:201], v[70:73]
	v_mfma_f32_16x16x32_bf16 v[66:69], v[166:169], v[198:201], v[66:69]
	v_mfma_f32_16x16x32_bf16 v[118:121], v[162:165], v[178:181], v[118:121]
	v_mfma_f32_16x16x32_bf16 v[114:117], v[170:173], v[178:181], v[114:117]
	v_mfma_f32_16x16x32_bf16 v[102:105], v[162:165], v[186:189], v[102:105]
	v_mfma_f32_16x16x32_bf16 v[98:101], v[170:173], v[186:189], v[98:101]
	v_mfma_f32_16x16x32_bf16 v[86:89], v[162:165], v[194:197], v[86:89]
	v_mfma_f32_16x16x32_bf16 v[82:85], v[170:173], v[194:197], v[82:85]
	v_mfma_f32_16x16x32_bf16 v[70:73], v[162:165], v[206:209], v[70:73]
	v_mfma_f32_16x16x32_bf16 v[66:69], v[170:173], v[206:209], v[66:69]
	s_setprio 0
	s_barrier
	s_add_i32 s39, s39, s23
	v_lshl_add_u64 v[210:211], s[18:19], 0, v[0:1]
	s_mov_b32 m0, s39
	ds_read_b128 v[174:177], v141 offset:16384
	ds_read_b128 v[178:181], v141 offset:17408
	ds_read_b128 v[182:185], v141 offset:18432
	ds_read_b128 v[186:189], v141 offset:19456
	ds_read_b128 v[190:193], v141 offset:20480
	ds_read_b128 v[194:197], v141 offset:21504
	ds_read_b128 v[198:201], v141 offset:22528
	ds_read_b128 v[206:209], v141 offset:23552
	global_load_lds_dwordx4 v[210:211], off
	s_add_i32 m0, s39, 0x2000
	s_add_u32 s40, s18, 0x40000
	v_lshl_add_u64 v[212:213], s[18:19], 0, v[130:131]
	s_addc_u32 s41, s19, 0
	s_add_i32 s39, s44, s23
	global_load_lds_dwordx4 v[212:213], off
	v_lshl_add_u64 v[214:215], s[40:41], 0, v[0:1]
	s_mov_b32 m0, s39
	v_lshl_add_u64 v[216:217], s[20:21], 0, v[132:133]
	global_load_lds_dwordx4 v[214:215], off
	s_add_i32 m0, s39, 0x2000
	v_lshl_add_u64 v[214:215], s[40:41], 0, v[130:131]
	global_load_lds_dwordx4 v[214:215], off
	s_mov_b32 m0, s25
	v_lshl_add_u64 v[214:215], s[20:21], 0, v[134:135]
	global_load_lds_dwordx4 v[214:215], off
	s_mov_b32 m0, s26
	s_nop 0
	global_load_lds_dwordx4 v[216:217], off
	s_waitcnt vmcnt(8)
	s_waitcnt lgkmcnt(0)
	s_barrier
; #define PG8_STAGE(bufoff, gbase, voff) do { _Pragma("unroll") for (int _i = 0; _i < 2; ++_i) \
;         __builtin_amdgcn_global_load_lds((const unsigned*)((const char*)(gbase) + (voff)[_i]), (PG8_LAS unsigned*)(lds + (bufoff) + ldsw + _i * 8192), 16, 0, 0); } while (0)
; #define PG8_LDA(dst, b, h) do { _Pragma("unroll") for (int m = 0; m < 4; ++m) _Pragma("unroll") for (int k = 0; k < 2; ++k) dst[m][k] = *(const PG8_LAS bf16x8*)(lds + PG8_SA(b, h) + aoff + m * 2048 + k * 1024); } while (0)
; #define PG8_LDB(dst, b, h) do { _Pragma("unroll") for (int n = 0; n < 2; ++n) _Pragma("unroll") for (int k = 0; k < 2; ++k) dst[n][k] = *(const PG8_LAS bf16x8*)(lds + PG8_SB(b, h) + boff + n * 2048 + k * 1024); } while (0)
; #define PG8_MMA(ai, bj, At, Bt) do { __builtin_amdgcn_s_setprio(1); _Pragma("unroll") for (int m = 0; m < 4; ++m) _Pragma("unroll") for (int n = 0; n < 2; ++n) _Pragma("unroll") for (int k = 0; k < 2; ++k) \
;         acc[ai][bj][m][n] = __builtin_amdgcn_mfma_f32_16x16x32_bf16(Bt[n][k], At[m][k], acc[ai][bj][m][n], 0, 0, 0); __builtin_amdgcn_s_setprio(0); } while (0)
; #define PG8_WAIT_V(n) asm volatile("s_waitcnt vmcnt(" #n ")" ::: "memory")
; #define PG8_WAIT_L(n) asm volatile("s_waitcnt lgkmcnt(" #n ")" ::: "memory")
; #define PG8_BAR __builtin_amdgcn_s_barrier()
; #define PG8_SCHED __builtin_amdgcn_sched_barrier(0)
; template <class Epi, class Sched, bool ALIGN_EPI = false, bool SP2 = false>
; __device__ __forceinline__ void gemm_phase(PG8_LAS unsigned char* lds, const Gemm g, const Sched& S, const Epi& E) {
;     ...
;             PG8_WAIT_V(8); PG8_WAIT_L(0); PG8_BAR; PG8_MMA(1, 0, At, B0); PG8_MMA(1, 1, At, B1); PG8_BAR; PG8_SCHED;
;             PG8_LDB(B0, 1, 0); PG8_LDB(B1, 1, 1); PG8_SCHED; PG8_LDA(At, 1, 0); PG8_STAGE(PG8_SA(0, 1), a2 + hstep, voffA);
;             PG8_WAIT_V(8); PG8_WAIT_L(0); PG8_BAR; PG8_MMA(0, 0, At, B0); PG8_MMA(0, 1, At, B1); PG8_BAR; PG8_SCHED;
	s_setprio 1
	s_waitcnt lgkmcnt(0)
	v_mfma_f32_16x16x32_bf16 v[62:65], v[142:145], v[174:177], v[62:65]
	v_mfma_f32_16x16x32_bf16 v[58:61], v[150:153], v[174:177], v[58:61]
	v_mfma_f32_16x16x32_bf16 v[46:49], v[142:145], v[182:185], v[46:49]
	v_mfma_f32_16x16x32_bf16 v[42:45], v[150:153], v[182:185], v[42:45]
	v_mfma_f32_16x16x32_bf16 v[30:33], v[142:145], v[190:193], v[30:33]
	v_mfma_f32_16x16x32_bf16 v[26:29], v[150:153], v[190:193], v[26:29]
	v_mfma_f32_16x16x32_bf16 v[14:17], v[142:145], v[198:201], v[14:17]
	v_mfma_f32_16x16x32_bf16 v[10:13], v[150:153], v[198:201], v[10:13]
	v_mfma_f32_16x16x32_bf16 v[62:65], v[146:149], v[178:181], v[62:65]
	v_mfma_f32_16x16x32_bf16 v[58:61], v[154:157], v[178:181], v[58:61]
	v_mfma_f32_16x16x32_bf16 v[46:49], v[146:149], v[186:189], v[46:49]
	v_mfma_f32_16x16x32_bf16 v[42:45], v[154:157], v[186:189], v[42:45]
	v_mfma_f32_16x16x32_bf16 v[30:33], v[146:149], v[194:197], v[30:33]
	v_mfma_f32_16x16x32_bf16 v[26:29], v[154:157], v[194:197], v[26:29]
	v_mfma_f32_16x16x32_bf16 v[14:17], v[146:149], v[206:209], v[14:17]
	v_mfma_f32_16x16x32_bf16 v[10:13], v[154:157], v[206:209], v[10:13]
	s_setprio 0
	s_setprio 1
	v_mfma_f32_16x16x32_bf16 v[54:57], v[158:161], v[174:177], v[54:57]
	v_mfma_f32_16x16x32_bf16 v[50:53], v[166:169], v[174:177], v[50:53]
	v_mfma_f32_16x16x32_bf16 v[38:41], v[158:161], v[182:185], v[38:41]
	v_mfma_f32_16x16x32_bf16 v[34:37], v[166:169], v[182:185], v[34:37]
	v_mfma_f32_16x16x32_bf16 v[22:25], v[158:161], v[190:193], v[22:25]
	v_mfma_f32_16x16x32_bf16 v[18:21], v[166:169], v[190:193], v[18:21]
	v_mfma_f32_16x16x32_bf16 v[6:9], v[158:161], v[198:201], v[6:9]
	v_mfma_f32_16x16x32_bf16 v[2:5], v[166:169], v[198:201], v[2:5]
	v_mfma_f32_16x16x32_bf16 v[54:57], v[162:165], v[178:181], v[54:57]
	v_mfma_f32_16x16x32_bf16 v[50:53], v[170:173], v[178:181], v[50:53]
	v_mfma_f32_16x16x32_bf16 v[38:41], v[162:165], v[186:189], v[38:41]
	v_mfma_f32_16x16x32_bf16 v[34:37], v[170:173], v[186:189], v[34:37]
	v_mfma_f32_16x16x32_bf16 v[22:25], v[162:165], v[194:197], v[22:25]
	v_mfma_f32_16x16x32_bf16 v[18:21], v[170:173], v[194:197], v[18:21]
	v_mfma_f32_16x16x32_bf16 v[6:9], v[162:165], v[206:209], v[6:9]
	v_mfma_f32_16x16x32_bf16 v[2:5], v[170:173], v[206:209], v[2:5]
	s_setprio 0
	s_barrier
	s_add_i32 s39, 0, 0x18000
	s_add_i32 s40, 0, 0x1c000
	v_add_u32_e32 v154, s39, v140
	v_add_u32_e32 v170, s40, v140
	ds_read_b128 v[142:145], v154
	ds_read_b128 v[146:149], v154 offset:1024
	ds_read_b128 v[150:153], v154 offset:2048
	ds_read_b128 v[154:157], v154 offset:3072
	ds_read_b128 v[158:161], v170
	ds_read_b128 v[162:165], v170 offset:1024
	ds_read_b128 v[166:169], v170 offset:2048
	ds_read_b128 v[170:173], v170 offset:3072
	s_add_u32 s20, s20, 0x40000
	s_addc_u32 s21, s21, 0
	s_mov_b32 m0, s27
	v_lshl_add_u64 v[218:219], s[20:21], 0, v[134:135]
	ds_read_b128 v[174:177], v141 offset:32768
	ds_read_b128 v[178:181], v141 offset:33792
	ds_read_b128 v[182:185], v141 offset:34816
	ds_read_b128 v[186:189], v141 offset:35840
	ds_read_b128 v[190:193], v141 offset:36864
	ds_read_b128 v[194:197], v141 offset:37888
	ds_read_b128 v[198:201], v141 offset:38912
	ds_read_b128 v[206:209], v141 offset:39936
	global_load_lds_dwordx4 v[218:219], off
	s_mov_b32 m0, s28
	v_lshl_add_u64 v[218:219], s[20:21], 0, v[132:133]
	global_load_lds_dwordx4 v[218:219], off
	s_waitcnt vmcnt(8)
	s_waitcnt lgkmcnt(0)
	s_barrier
	s_setprio 1
	s_waitcnt lgkmcnt(0)
	v_mfma_f32_16x16x32_bf16 v[126:129], v[142:145], v[174:177], v[126:129]
	v_mfma_f32_16x16x32_bf16 v[122:125], v[150:153], v[174:177], v[122:125]
	v_mfma_f32_16x16x32_bf16 v[110:113], v[142:145], v[182:185], v[110:113]
	v_mfma_f32_16x16x32_bf16 v[106:109], v[150:153], v[182:185], v[106:109]
	v_mfma_f32_16x16x32_bf16 v[94:97], v[142:145], v[190:193], v[94:97]
	v_mfma_f32_16x16x32_bf16 v[90:93], v[150:153], v[190:193], v[90:93]
	v_mfma_f32_16x16x32_bf16 v[78:81], v[142:145], v[198:201], v[78:81]
	v_mfma_f32_16x16x32_bf16 v[74:77], v[150:153], v[198:201], v[74:77]
	v_mfma_f32_16x16x32_bf16 v[126:129], v[146:149], v[178:181], v[126:129]
	v_mfma_f32_16x16x32_bf16 v[122:125], v[154:157], v[178:181], v[122:125]
	v_mfma_f32_16x16x32_bf16 v[110:113], v[146:149], v[186:189], v[110:113]
	v_mfma_f32_16x16x32_bf16 v[106:109], v[154:157], v[186:189], v[106:109]
	v_mfma_f32_16x16x32_bf16 v[94:97], v[146:149], v[194:197], v[94:97]
	v_mfma_f32_16x16x32_bf16 v[90:93], v[154:157], v[194:197], v[90:93]
	v_mfma_f32_16x16x32_bf16 v[78:81], v[146:149], v[206:209], v[78:81]
	v_mfma_f32_16x16x32_bf16 v[74:77], v[154:157], v[206:209], v[74:77]
	s_setprio 0
	s_setprio 1
	v_mfma_f32_16x16x32_bf16 v[118:121], v[158:161], v[174:177], v[118:121]
	v_mfma_f32_16x16x32_bf16 v[114:117], v[166:169], v[174:177], v[114:117]
	v_mfma_f32_16x16x32_bf16 v[102:105], v[158:161], v[182:185], v[102:105]
	v_mfma_f32_16x16x32_bf16 v[98:101], v[166:169], v[182:185], v[98:101]
	v_mfma_f32_16x16x32_bf16 v[86:89], v[158:161], v[190:193], v[86:89]
	v_mfma_f32_16x16x32_bf16 v[82:85], v[166:169], v[190:193], v[82:85]
	v_mfma_f32_16x16x32_bf16 v[70:73], v[158:161], v[198:201], v[70:73]
	v_mfma_f32_16x16x32_bf16 v[66:69], v[166:169], v[198:201], v[66:69]
	v_mfma_f32_16x16x32_bf16 v[118:121], v[162:165], v[178:181], v[118:121]
	v_mfma_f32_16x16x32_bf16 v[114:117], v[170:173], v[178:181], v[114:117]
	v_mfma_f32_16x16x32_bf16 v[102:105], v[162:165], v[186:189], v[102:105]
	v_mfma_f32_16x16x32_bf16 v[98:101], v[170:173], v[186:189], v[98:101]
	v_mfma_f32_16x16x32_bf16 v[86:89], v[162:165], v[194:197], v[86:89]
	v_mfma_f32_16x16x32_bf16 v[82:85], v[170:173], v[194:197], v[82:85]
	v_mfma_f32_16x16x32_bf16 v[70:73], v[162:165], v[206:209], v[70:73]
	v_mfma_f32_16x16x32_bf16 v[66:69], v[170:173], v[206:209], v[66:69]
	s_setprio 0
	s_barrier
; #define PG8_STAGE(bufoff, gbase, voff) do { _Pragma("unroll") for (int _i = 0; _i < 2; ++_i) \
;         __builtin_amdgcn_global_load_lds((const unsigned*)((const char*)(gbase) + (voff)[_i]), (PG8_LAS unsigned*)(lds + (bufoff) + ldsw + _i * 8192), 16, 0, 0); } while (0)
; #define PG8_LDA(dst, b, h) do { _Pragma("unroll") for (int m = 0; m < 4; ++m) _Pragma("unroll") for (int k = 0; k < 2; ++k) dst[m][k] = *(const PG8_LAS bf16x8*)(lds + PG8_SA(b, h) + aoff + m * 2048 + k * 1024); } while (0)
; #define PG8_MMA(ai, bj, At, Bt) do { __builtin_amdgcn_s_setprio(1); _Pragma("unroll") for (int m = 0; m < 4; ++m) _Pragma("unroll") for (int n = 0; n < 2; ++n) _Pragma("unroll") for (int k = 0; k < 2; ++k) \
;         acc[ai][bj][m][n] = __builtin_amdgcn_mfma_f32_16x16x32_bf16(Bt[n][k], At[m][k], acc[ai][bj][m][n], 0, 0, 0); __builtin_amdgcn_s_setprio(0); } while (0)
; #define PG8_WAIT_V(n) asm volatile("s_waitcnt vmcnt(" #n ")" ::: "memory")
; #define PG8_WAIT_L(n) asm volatile("s_waitcnt lgkmcnt(" #n ")" ::: "memory")
; #define PG8_BAR __builtin_amdgcn_s_barrier()
; #define PG8_SCHED __builtin_amdgcn_sched_barrier(0)
; template <class Epi, class Sched, bool ALIGN_EPI = false, bool SP2 = false>
; __device__ __forceinline__ void gemm_phase(PG8_LAS unsigned char* lds, const Gemm g, const Sched& S, const Epi& E) {
;     ...
;             PG8_LDA(At, 1, 1); PG8_STAGE(PG8_SB(1, 0), b3, voffB); PG8_STAGE(PG8_SB(1, 1), b3 + hstep, voffB); PG8_STAGE(PG8_SA(1, 0), a3, voffA);
;             PG8_WAIT_V(8); PG8_WAIT_L(0); PG8_BAR; PG8_MMA(1, 0, At, B0); PG8_MMA(1, 1, At, B1); PG8_BAR; PG8_SCHED;
;     ...
;         if constexpr (ALIGN_EPI) { if (wr == 0) PG8_BAR; }
	s_add_i32 s20, s39, s23
	v_lshl_add_u64 v[210:211], v[210:211], 0, s[48:49]
	s_mov_b32 m0, s20
	ds_read_b128 v[174:177], v141 offset:49152
	ds_read_b128 v[178:181], v141 offset:50176
	ds_read_b128 v[182:185], v141 offset:51200
	ds_read_b128 v[186:189], v141 offset:52224
	ds_read_b128 v[190:193], v141 offset:53248
	ds_read_b128 v[194:197], v141 offset:54272
	ds_read_b128 v[198:201], v141 offset:55296
	ds_read_b128 v[206:209], v141 offset:56320
	global_load_lds_dwordx4 v[210:211], off
	s_add_i32 m0, s20, 0x2000
	s_add_u32 s18, s18, 0x40080
	v_lshl_add_u64 v[210:211], v[212:213], 0, s[48:49]
	s_addc_u32 s19, s19, 0
	s_add_i32 s20, s40, s23
	global_load_lds_dwordx4 v[210:211], off
	s_mov_b32 m0, s20
	v_lshl_add_u64 v[210:211], s[18:19], 0, v[0:1]
	global_load_lds_dwordx4 v[210:211], off
	s_add_i32 m0, s20, 0x2000
	v_lshl_add_u64 v[210:211], s[18:19], 0, v[130:131]
	global_load_lds_dwordx4 v[210:211], off
	s_mov_b32 m0, s29
	v_lshl_add_u64 v[210:211], v[214:215], 0, s[48:49]
	global_load_lds_dwordx4 v[210:211], off
	s_mov_b32 m0, s30
	v_lshl_add_u64 v[210:211], v[216:217], 0, s[48:49]
	global_load_lds_dwordx4 v[210:211], off
	s_waitcnt vmcnt(8)
	s_waitcnt lgkmcnt(0)
	s_barrier
	s_setprio 1
	s_waitcnt lgkmcnt(0)
	v_mfma_f32_16x16x32_bf16 v[62:65], v[142:145], v[174:177], v[62:65]
	v_mfma_f32_16x16x32_bf16 v[58:61], v[150:153], v[174:177], v[58:61]
	v_mfma_f32_16x16x32_bf16 v[46:49], v[142:145], v[182:185], v[46:49]
	v_mfma_f32_16x16x32_bf16 v[42:45], v[150:153], v[182:185], v[42:45]
	v_mfma_f32_16x16x32_bf16 v[30:33], v[142:145], v[190:193], v[30:33]
	v_mfma_f32_16x16x32_bf16 v[26:29], v[150:153], v[190:193], v[26:29]
	v_mfma_f32_16x16x32_bf16 v[14:17], v[142:145], v[198:201], v[14:17]
	v_mfma_f32_16x16x32_bf16 v[10:13], v[150:153], v[198:201], v[10:13]
	v_mfma_f32_16x16x32_bf16 v[62:65], v[146:149], v[178:181], v[62:65]
	v_mfma_f32_16x16x32_bf16 v[58:61], v[154:157], v[178:181], v[58:61]
	v_mfma_f32_16x16x32_bf16 v[46:49], v[146:149], v[186:189], v[46:49]
	v_mfma_f32_16x16x32_bf16 v[42:45], v[154:157], v[186:189], v[42:45]
	v_mfma_f32_16x16x32_bf16 v[30:33], v[146:149], v[194:197], v[30:33]
	v_mfma_f32_16x16x32_bf16 v[26:29], v[154:157], v[194:197], v[26:29]
	v_mfma_f32_16x16x32_bf16 v[14:17], v[146:149], v[206:209], v[14:17]
	v_mfma_f32_16x16x32_bf16 v[10:13], v[154:157], v[206:209], v[10:13]
	s_setprio 0
	s_setprio 1
	v_mfma_f32_16x16x32_bf16 v[54:57], v[158:161], v[174:177], v[54:57]
	v_mfma_f32_16x16x32_bf16 v[50:53], v[166:169], v[174:177], v[50:53]
	v_mfma_f32_16x16x32_bf16 v[38:41], v[158:161], v[182:185], v[38:41]
	v_mfma_f32_16x16x32_bf16 v[34:37], v[166:169], v[182:185], v[34:37]
	v_mfma_f32_16x16x32_bf16 v[22:25], v[158:161], v[190:193], v[22:25]
	v_mfma_f32_16x16x32_bf16 v[18:21], v[166:169], v[190:193], v[18:21]
	v_mfma_f32_16x16x32_bf16 v[6:9], v[158:161], v[198:201], v[6:9]
	v_mfma_f32_16x16x32_bf16 v[2:5], v[166:169], v[198:201], v[2:5]
	v_mfma_f32_16x16x32_bf16 v[54:57], v[162:165], v[178:181], v[54:57]
	v_mfma_f32_16x16x32_bf16 v[50:53], v[170:173], v[178:181], v[50:53]
	v_mfma_f32_16x16x32_bf16 v[38:41], v[162:165], v[186:189], v[38:41]
	v_mfma_f32_16x16x32_bf16 v[34:37], v[170:173], v[186:189], v[34:37]
	v_mfma_f32_16x16x32_bf16 v[22:25], v[162:165], v[194:197], v[22:25]
	v_mfma_f32_16x16x32_bf16 v[18:21], v[170:173], v[194:197], v[18:21]
	v_mfma_f32_16x16x32_bf16 v[6:9], v[162:165], v[206:209], v[6:9]
	v_mfma_f32_16x16x32_bf16 v[2:5], v[170:173], v[206:209], v[2:5]
	s_setprio 0
	s_barrier
	s_add_i32 s38, s38, 2
	s_add_u32 s16, s16, 0x100
	s_addc_u32 s17, s17, 0
	s_add_u32 s36, s36, 0x100
	s_addc_u32 s37, s37, 0
	s_cmp_gt_u32 s38, 13
	s_cbranch_scc0 .LBB0_71
	s_and_b64 vcc, exec, s[4:5]
	s_cbranch_vccz .LBB0_74
	s_barrier

; #define PG8_STAGE(bufoff, gbase, voff) do { _Pragma("unroll") for (int _i = 0; _i < 2; ++_i) \
;         __builtin_amdgcn_global_load_lds((const unsigned*)((const char*)(gbase) + (voff)[_i]), (PG8_LAS unsigned*)(lds + (bufoff) + ldsw + _i * 8192), 16, 0, 0); } while (0)
; #define PG8_LDA(dst, b, h) do { _Pragma("unroll") for (int m = 0; m < 4; ++m) _Pragma("unroll") for (int k = 0; k < 2; ++k) dst[m][k] = *(const PG8_LAS bf16x8*)(lds + PG8_SA(b, h) + aoff + m * 2048 + k * 1024); } while (0)
; #define PG8_LDB(dst, b, h) do { _Pragma("unroll") for (int n = 0; n < 2; ++n) _Pragma("unroll") for (int k = 0; k < 2; ++k) dst[n][k] = *(const PG8_LAS bf16x8*)(lds + PG8_SB(b, h) + boff + n * 2048 + k * 1024); } while (0)
; #define PG8_MMA(ai, bj, At, Bt) do { __builtin_amdgcn_s_setprio(1); _Pragma("unroll") for (int m = 0; m < 4; ++m) _Pragma("unroll") for (int n = 0; n < 2; ++n) _Pragma("unroll") for (int k = 0; k < 2; ++k) \
;         acc[ai][bj][m][n] = __builtin_amdgcn_mfma_f32_16x16x32_bf16(Bt[n][k], At[m][k], acc[ai][bj][m][n], 0, 0, 0); __builtin_amdgcn_s_setprio(0); } while (0)
; #define PG8_WAIT_V(n) asm volatile("s_waitcnt vmcnt(" #n ")" ::: "memory")
; #define PG8_WAIT_L(n) asm volatile("s_waitcnt lgkmcnt(" #n ")" ::: "memory")
; #define PG8_BAR __builtin_amdgcn_s_barrier()
; #define PG8_SCHED __builtin_amdgcn_sched_barrier(0)
; template <class Epi, class Sched, bool ALIGN_EPI = false, bool SP2 = false>
; __device__ __forceinline__ void gemm_phase(PG8_LAS unsigned char* lds, const Gemm g, const Sched& S, const Epi& E) {
;     ...
;         for (int t = 0; t < nt; t += 2) {
;             const bool last = (t == nt - 2);
;             const char* a1 = cA + (size_t)(t + 1) * kstep;
;             const char* a2 = last ? nA : cA + (size_t)(t + 2) * kstep; const char* b2 = last ? nB : cB + (size_t)(t + 2) * kstep;
;             const char* a3 = a2 + kstep; const char* b3 = b2 + kstep;
;             if (last && has_next) S.a_ready(nxt);
;             if constexpr (SP2) {
;             PG8_LDB(B0, 0, 0); PG8_LDB(B1, 0, 1); PG8_SCHED; PG8_LDA(At, 0, 0); PG8_STAGE(PG8_SA(1, 1), a1 + hstep, voffA);
;             PG8_WAIT_V(8); PG8_WAIT_L(0); PG8_BAR; PG8_MMA(0, 0, At, B0); PG8_MMA(0, 1, At, B1); PG8_BAR; PG8_SCHED;
;             PG8_LDA(At, 0, 1); PG8_STAGE(PG8_SB(0, 0), b2, voffB); PG8_STAGE(PG8_SB(0, 1), b2 + hstep, voffB); PG8_STAGE(PG8_SA(0, 0), a2, voffA);
.LBB0_147:
	s_add_u32 s6, s4, 0xfffc0080
	s_addc_u32 s7, s5, -1
	s_cmp_eq_u32 s39, 12
	s_cselect_b32 s9, s11, s7
	s_cselect_b32 s8, s19, s6
	s_cselect_b32 s7, s27, s38
	s_cselect_b32 s6, s29, s31
	s_add_i32 s40, 0, 0x10000
	v_add_u32_e32 v0, s40, v176
	s_add_i32 s44, 0, 0x14000
	ds_read_b128 v[58:61], v0
	ds_read_b128 v[62:65], v0 offset:1024
	ds_read_b128 v[66:69], v0 offset:2048
	ds_read_b128 v[70:73], v0 offset:3072
	v_add_u32_e32 v0, s44, v176
	ds_read_b128 v[74:77], v0
	ds_read_b128 v[78:81], v0 offset:1024
	ds_read_b128 v[82:85], v0 offset:2048
	ds_read_b128 v[172:175], v0 offset:3072
	v_lshl_add_u64 v[86:87], s[4:5], 0, v[168:169]
	s_add_i32 m0, s12, 0xc000
	ds_read_b128 v[178:181], v177
	ds_read_b128 v[182:185], v177 offset:1024
	ds_read_b128 v[186:189], v177 offset:2048
	ds_read_b128 v[190:193], v177 offset:3072
	ds_read_b128 v[194:197], v177 offset:4096
	ds_read_b128 v[198:201], v177 offset:5120
	ds_read_b128 v[206:209], v177 offset:6144
	ds_read_b128 v[210:213], v177 offset:7168
	global_load_lds_dwordx4 v[86:87], off
	s_add_i32 m0, s12, 0xe000
	v_lshl_add_u64 v[86:87], s[4:5], 0, v[170:171]
	global_load_lds_dwordx4 v[86:87], off
	s_waitcnt vmcnt(8)
	s_waitcnt lgkmcnt(0)
	s_barrier
	s_setprio 1
	s_waitcnt lgkmcnt(0)
	v_mfma_f32_16x16x32_bf16 v[156:159], v[58:61], v[178:181], v[156:159]
	v_mfma_f32_16x16x32_bf16 v[152:155], v[66:69], v[178:181], v[152:155]
	v_mfma_f32_16x16x32_bf16 v[140:143], v[58:61], v[186:189], v[140:143]
	v_mfma_f32_16x16x32_bf16 v[136:139], v[66:69], v[186:189], v[136:139]
	v_mfma_f32_16x16x32_bf16 v[124:127], v[58:61], v[194:197], v[124:127]
	v_mfma_f32_16x16x32_bf16 v[120:123], v[66:69], v[194:197], v[120:123]
	v_mfma_f32_16x16x32_bf16 v[108:111], v[58:61], v[206:209], v[108:111]
	v_mfma_f32_16x16x32_bf16 v[104:107], v[66:69], v[206:209], v[104:107]
	v_mfma_f32_16x16x32_bf16 v[156:159], v[62:65], v[182:185], v[156:159]
	v_mfma_f32_16x16x32_bf16 v[152:155], v[70:73], v[182:185], v[152:155]
	v_mfma_f32_16x16x32_bf16 v[140:143], v[62:65], v[190:193], v[140:143]
	v_mfma_f32_16x16x32_bf16 v[136:139], v[70:73], v[190:193], v[136:139]
	v_mfma_f32_16x16x32_bf16 v[124:127], v[62:65], v[198:201], v[124:127]
	v_mfma_f32_16x16x32_bf16 v[120:123], v[70:73], v[198:201], v[120:123]
	v_mfma_f32_16x16x32_bf16 v[108:111], v[62:65], v[210:213], v[108:111]
	v_mfma_f32_16x16x32_bf16 v[104:107], v[70:73], v[210:213], v[104:107]
	s_setprio 0
	s_setprio 1
	v_mfma_f32_16x16x32_bf16 v[148:151], v[74:77], v[178:181], v[148:151]
	v_mfma_f32_16x16x32_bf16 v[144:147], v[82:85], v[178:181], v[144:147]
	v_mfma_f32_16x16x32_bf16 v[132:135], v[74:77], v[186:189], v[132:135]
	v_mfma_f32_16x16x32_bf16 v[128:131], v[82:85], v[186:189], v[128:131]
	v_mfma_f32_16x16x32_bf16 v[116:119], v[74:77], v[194:197], v[116:119]
	v_mfma_f32_16x16x32_bf16 v[112:115], v[82:85], v[194:197], v[112:115]
	v_mfma_f32_16x16x32_bf16 v[100:103], v[74:77], v[206:209], v[100:103]
	v_mfma_f32_16x16x32_bf16 v[96:99], v[82:85], v[206:209], v[96:99]
	v_mfma_f32_16x16x32_bf16 v[148:151], v[78:81], v[182:185], v[148:151]
	v_mfma_f32_16x16x32_bf16 v[144:147], v[172:175], v[182:185], v[144:147]
	v_mfma_f32_16x16x32_bf16 v[132:135], v[78:81], v[190:193], v[132:135]
	v_mfma_f32_16x16x32_bf16 v[128:131], v[172:175], v[190:193], v[128:131]
	v_mfma_f32_16x16x32_bf16 v[116:119], v[78:81], v[198:201], v[116:119]
	v_mfma_f32_16x16x32_bf16 v[112:115], v[172:175], v[198:201], v[112:115]
	v_mfma_f32_16x16x32_bf16 v[100:103], v[78:81], v[210:213], v[100:103]
	v_mfma_f32_16x16x32_bf16 v[96:99], v[172:175], v[210:213], v[96:99]
	s_setprio 0
	s_barrier
	s_add_i32 s40, s40, s2
	v_lshl_add_u64 v[214:215], s[6:7], 0, v[164:165]
	s_mov_b32 m0, s40
	ds_read_b128 v[178:181], v177 offset:16384
	ds_read_b128 v[182:185], v177 offset:17408
	ds_read_b128 v[186:189], v177 offset:18432
	ds_read_b128 v[190:193], v177 offset:19456
	ds_read_b128 v[194:197], v177 offset:20480
	ds_read_b128 v[198:201], v177 offset:21504
	ds_read_b128 v[206:209], v177 offset:22528
	ds_read_b128 v[210:213], v177 offset:23552
	global_load_lds_dwordx4 v[214:215], off
	s_add_i32 m0, s40, 0x2000
	s_add_u32 s40, s6, 0x40000
	v_lshl_add_u64 v[216:217], s[6:7], 0, v[160:161]
	s_addc_u32 s41, s7, 0
	s_add_i32 s44, s44, s2
	global_load_lds_dwordx4 v[216:217], off
	v_lshl_add_u64 v[86:87], s[40:41], 0, v[164:165]
	s_mov_b32 m0, s44
	v_lshl_add_u64 v[218:219], s[8:9], 0, v[166:167]
	global_load_lds_dwordx4 v[86:87], off
	v_lshl_add_u64 v[86:87], s[40:41], 0, v[160:161]
	s_add_i32 m0, s44, 0x2000
	v_lshl_add_u64 v[220:221], s[8:9], 0, v[162:163]
	global_load_lds_dwordx4 v[86:87], off
	s_mov_b32 m0, s12
	s_nop 0
	global_load_lds_dwordx4 v[218:219], off
	s_mov_b32 m0, s13
	s_nop 0
	global_load_lds_dwordx4 v[220:221], off
	s_waitcnt vmcnt(8)
	s_waitcnt lgkmcnt(0)
	s_barrier
; #define PG8_STAGE(bufoff, gbase, voff) do { _Pragma("unroll") for (int _i = 0; _i < 2; ++_i) \
;         __builtin_amdgcn_global_load_lds((const unsigned*)((const char*)(gbase) + (voff)[_i]), (PG8_LAS unsigned*)(lds + (bufoff) + ldsw + _i * 8192), 16, 0, 0); } while (0)
; #define PG8_LDA(dst, b, h) do { _Pragma("unroll") for (int m = 0; m < 4; ++m) _Pragma("unroll") for (int k = 0; k < 2; ++k) dst[m][k] = *(const PG8_LAS bf16x8*)(lds + PG8_SA(b, h) + aoff + m * 2048 + k * 1024); } while (0)
; #define PG8_LDB(dst, b, h) do { _Pragma("unroll") for (int n = 0; n < 2; ++n) _Pragma("unroll") for (int k = 0; k < 2; ++k) dst[n][k] = *(const PG8_LAS bf16x8*)(lds + PG8_SB(b, h) + boff + n * 2048 + k * 1024); } while (0)
; #define PG8_MMA(ai, bj, At, Bt) do { __builtin_amdgcn_s_setprio(1); _Pragma("unroll") for (int m = 0; m < 4; ++m) _Pragma("unroll") for (int n = 0; n < 2; ++n) _Pragma("unroll") for (int k = 0; k < 2; ++k) \
;         acc[ai][bj][m][n] = __builtin_amdgcn_mfma_f32_16x16x32_bf16(Bt[n][k], At[m][k], acc[ai][bj][m][n], 0, 0, 0); __builtin_amdgcn_s_setprio(0); } while (0)
; #define PG8_WAIT_V(n) asm volatile("s_waitcnt vmcnt(" #n ")" ::: "memory")
; #define PG8_WAIT_L(n) asm volatile("s_waitcnt lgkmcnt(" #n ")" ::: "memory")
; #define PG8_BAR __builtin_amdgcn_s_barrier()
; #define PG8_SCHED __builtin_amdgcn_sched_barrier(0)
; template <class Epi, class Sched, bool ALIGN_EPI = false, bool SP2 = false>
; __device__ __forceinline__ void gemm_phase(PG8_LAS unsigned char* lds, const Gemm g, const Sched& S, const Epi& E) {
;     ...
;             PG8_WAIT_V(8); PG8_WAIT_L(0); PG8_BAR; PG8_MMA(1, 0, At, B0); PG8_MMA(1, 1, At, B1); PG8_BAR; PG8_SCHED;
;             PG8_LDB(B0, 1, 0); PG8_LDB(B1, 1, 1); PG8_SCHED; PG8_LDA(At, 1, 0); PG8_STAGE(PG8_SA(0, 1), a2 + hstep, voffA);
;             PG8_WAIT_V(8); PG8_WAIT_L(0); PG8_BAR; PG8_MMA(0, 0, At, B0); PG8_MMA(0, 1, At, B1); PG8_BAR; PG8_SCHED;
	s_setprio 1
	s_waitcnt lgkmcnt(0)
	v_mfma_f32_16x16x32_bf16 v[92:95], v[58:61], v[178:181], v[92:95]
	v_mfma_f32_16x16x32_bf16 v[86:89], v[66:69], v[178:181], v[88:91]
	v_mfma_f32_16x16x32_bf16 v[46:49], v[58:61], v[186:189], v[46:49]
	v_mfma_f32_16x16x32_bf16 v[42:45], v[66:69], v[186:189], v[42:45]
	v_mfma_f32_16x16x32_bf16 v[30:33], v[58:61], v[194:197], v[30:33]
	v_mfma_f32_16x16x32_bf16 v[26:29], v[66:69], v[194:197], v[26:29]
	v_mfma_f32_16x16x32_bf16 v[14:17], v[58:61], v[206:209], v[14:17]
	v_mfma_f32_16x16x32_bf16 v[10:13], v[66:69], v[206:209], v[10:13]
	v_mfma_f32_16x16x32_bf16 v[92:95], v[62:65], v[182:185], v[92:95]
	v_mfma_f32_16x16x32_bf16 v[86:89], v[70:73], v[182:185], v[86:89]
	v_mfma_f32_16x16x32_bf16 v[46:49], v[62:65], v[190:193], v[46:49]
	v_mfma_f32_16x16x32_bf16 v[42:45], v[70:73], v[190:193], v[42:45]
	v_mfma_f32_16x16x32_bf16 v[30:33], v[62:65], v[198:201], v[30:33]
	v_mfma_f32_16x16x32_bf16 v[26:29], v[70:73], v[198:201], v[26:29]
	v_mfma_f32_16x16x32_bf16 v[14:17], v[62:65], v[210:213], v[14:17]
	v_mfma_f32_16x16x32_bf16 v[10:13], v[70:73], v[210:213], v[10:13]
	s_setprio 0
	s_setprio 1
	v_mfma_f32_16x16x32_bf16 v[54:57], v[74:77], v[178:181], v[54:57]
	v_mfma_f32_16x16x32_bf16 v[50:53], v[82:85], v[178:181], v[50:53]
	v_mfma_f32_16x16x32_bf16 v[38:41], v[74:77], v[186:189], v[38:41]
	v_mfma_f32_16x16x32_bf16 v[34:37], v[82:85], v[186:189], v[34:37]
	v_mfma_f32_16x16x32_bf16 v[22:25], v[74:77], v[194:197], v[22:25]
	v_mfma_f32_16x16x32_bf16 v[18:21], v[82:85], v[194:197], v[18:21]
	v_mfma_f32_16x16x32_bf16 v[6:9], v[74:77], v[206:209], v[6:9]
	v_mfma_f32_16x16x32_bf16 v[2:5], v[82:85], v[206:209], v[2:5]
	v_mfma_f32_16x16x32_bf16 v[54:57], v[78:81], v[182:185], v[54:57]
	v_mfma_f32_16x16x32_bf16 v[50:53], v[172:175], v[182:185], v[50:53]
	v_mfma_f32_16x16x32_bf16 v[38:41], v[78:81], v[190:193], v[38:41]
	v_mfma_f32_16x16x32_bf16 v[34:37], v[172:175], v[190:193], v[34:37]
	v_mfma_f32_16x16x32_bf16 v[22:25], v[78:81], v[198:201], v[22:25]
	v_mfma_f32_16x16x32_bf16 v[18:21], v[172:175], v[198:201], v[18:21]
	v_mfma_f32_16x16x32_bf16 v[6:9], v[78:81], v[210:213], v[6:9]
	v_mfma_f32_16x16x32_bf16 v[2:5], v[172:175], v[210:213], v[2:5]
	s_setprio 0
	s_barrier
	s_add_i32 s40, 0, 0x18000
	v_add_u32_e32 v0, s40, v176
	s_add_i32 s41, 0, 0x1c000
	ds_read_b128 v[58:61], v0
	ds_read_b128 v[62:65], v0 offset:1024
	ds_read_b128 v[66:69], v0 offset:2048
	ds_read_b128 v[70:73], v0 offset:3072
	v_add_u32_e32 v0, s41, v176
	ds_read_b128 v[74:77], v0
	ds_read_b128 v[78:81], v0 offset:1024
	ds_read_b128 v[82:85], v0 offset:2048
	ds_read_b128 v[172:175], v0 offset:3072
	s_add_u32 s8, s8, 0x40000
	s_addc_u32 s9, s9, 0
	s_mov_b32 m0, s14
	v_lshl_add_u64 v[90:91], s[8:9], 0, v[166:167]
	ds_read_b128 v[178:181], v177 offset:32768
	ds_read_b128 v[182:185], v177 offset:33792
	ds_read_b128 v[186:189], v177 offset:34816
	ds_read_b128 v[190:193], v177 offset:35840
	ds_read_b128 v[194:197], v177 offset:36864
	ds_read_b128 v[198:201], v177 offset:37888
	ds_read_b128 v[206:209], v177 offset:38912
	ds_read_b128 v[210:213], v177 offset:39936
	global_load_lds_dwordx4 v[90:91], off
	s_mov_b32 m0, s15
	v_lshl_add_u64 v[90:91], s[8:9], 0, v[162:163]
	global_load_lds_dwordx4 v[90:91], off
	s_waitcnt vmcnt(8)
	s_waitcnt lgkmcnt(0)
	s_barrier
	s_setprio 1
	s_waitcnt lgkmcnt(0)
	v_mfma_f32_16x16x32_bf16 v[156:159], v[58:61], v[178:181], v[156:159]
	v_mfma_f32_16x16x32_bf16 v[152:155], v[66:69], v[178:181], v[152:155]
	v_mfma_f32_16x16x32_bf16 v[140:143], v[58:61], v[186:189], v[140:143]
	v_mfma_f32_16x16x32_bf16 v[136:139], v[66:69], v[186:189], v[136:139]
	v_mfma_f32_16x16x32_bf16 v[124:127], v[58:61], v[194:197], v[124:127]
	v_mfma_f32_16x16x32_bf16 v[120:123], v[66:69], v[194:197], v[120:123]
	v_mfma_f32_16x16x32_bf16 v[108:111], v[58:61], v[206:209], v[108:111]
	v_mfma_f32_16x16x32_bf16 v[104:107], v[66:69], v[206:209], v[104:107]
	v_mfma_f32_16x16x32_bf16 v[156:159], v[62:65], v[182:185], v[156:159]
	v_mfma_f32_16x16x32_bf16 v[152:155], v[70:73], v[182:185], v[152:155]
	v_mfma_f32_16x16x32_bf16 v[140:143], v[62:65], v[190:193], v[140:143]
	v_mfma_f32_16x16x32_bf16 v[136:139], v[70:73], v[190:193], v[136:139]
	v_mfma_f32_16x16x32_bf16 v[124:127], v[62:65], v[198:201], v[124:127]
	v_mfma_f32_16x16x32_bf16 v[120:123], v[70:73], v[198:201], v[120:123]
	v_mfma_f32_16x16x32_bf16 v[108:111], v[62:65], v[210:213], v[108:111]
	v_mfma_f32_16x16x32_bf16 v[104:107], v[70:73], v[210:213], v[104:107]
	s_setprio 0
	s_setprio 1
	v_mfma_f32_16x16x32_bf16 v[148:151], v[74:77], v[178:181], v[148:151]
	v_mfma_f32_16x16x32_bf16 v[144:147], v[82:85], v[178:181], v[144:147]
	v_mfma_f32_16x16x32_bf16 v[132:135], v[74:77], v[186:189], v[132:135]
	v_mfma_f32_16x16x32_bf16 v[128:131], v[82:85], v[186:189], v[128:131]
	v_mfma_f32_16x16x32_bf16 v[116:119], v[74:77], v[194:197], v[116:119]
	v_mfma_f32_16x16x32_bf16 v[112:115], v[82:85], v[194:197], v[112:115]
	v_mfma_f32_16x16x32_bf16 v[100:103], v[74:77], v[206:209], v[100:103]
	v_mfma_f32_16x16x32_bf16 v[96:99], v[82:85], v[206:209], v[96:99]
	v_mfma_f32_16x16x32_bf16 v[148:151], v[78:81], v[182:185], v[148:151]
	v_mfma_f32_16x16x32_bf16 v[144:147], v[172:175], v[182:185], v[144:147]
	v_mfma_f32_16x16x32_bf16 v[132:135], v[78:81], v[190:193], v[132:135]
	v_mfma_f32_16x16x32_bf16 v[128:131], v[172:175], v[190:193], v[128:131]
	v_mfma_f32_16x16x32_bf16 v[116:119], v[78:81], v[198:201], v[116:119]
	v_mfma_f32_16x16x32_bf16 v[112:115], v[172:175], v[198:201], v[112:115]
	v_mfma_f32_16x16x32_bf16 v[100:103], v[78:81], v[210:213], v[100:103]
	v_mfma_f32_16x16x32_bf16 v[96:99], v[172:175], v[210:213], v[96:99]
	s_setprio 0
	s_barrier
; #define PG8_STAGE(bufoff, gbase, voff) do { _Pragma("unroll") for (int _i = 0; _i < 2; ++_i) \
;         __builtin_amdgcn_global_load_lds((const unsigned*)((const char*)(gbase) + (voff)[_i]), (PG8_LAS unsigned*)(lds + (bufoff) + ldsw + _i * 8192), 16, 0, 0); } while (0)
; #define PG8_LDA(dst, b, h) do { _Pragma("unroll") for (int m = 0; m < 4; ++m) _Pragma("unroll") for (int k = 0; k < 2; ++k) dst[m][k] = *(const PG8_LAS bf16x8*)(lds + PG8_SA(b, h) + aoff + m * 2048 + k * 1024); } while (0)
; #define PG8_MMA(ai, bj, At, Bt) do { __builtin_amdgcn_s_setprio(1); _Pragma("unroll") for (int m = 0; m < 4; ++m) _Pragma("unroll") for (int n = 0; n < 2; ++n) _Pragma("unroll") for (int k = 0; k < 2; ++k) \
;         acc[ai][bj][m][n] = __builtin_amdgcn_mfma_f32_16x16x32_bf16(Bt[n][k], At[m][k], acc[ai][bj][m][n], 0, 0, 0); __builtin_amdgcn_s_setprio(0); } while (0)
; #define PG8_WAIT_V(n) asm volatile("s_waitcnt vmcnt(" #n ")" ::: "memory")
; #define PG8_WAIT_L(n) asm volatile("s_waitcnt lgkmcnt(" #n ")" ::: "memory")
; #define PG8_BAR __builtin_amdgcn_s_barrier()
; #define PG8_SCHED __builtin_amdgcn_sched_barrier(0)
; template <class Epi, class Sched, bool ALIGN_EPI = false, bool SP2 = false>
; __device__ __forceinline__ void gemm_phase(PG8_LAS unsigned char* lds, const Gemm g, const Sched& S, const Epi& E) {
;     ...
;             PG8_LDA(At, 1, 1); PG8_STAGE(PG8_SB(1, 0), b3, voffB); PG8_STAGE(PG8_SB(1, 1), b3 + hstep, voffB); PG8_STAGE(PG8_SA(1, 0), a3, voffA);
;             PG8_WAIT_V(8); PG8_WAIT_L(0); PG8_BAR; PG8_MMA(1, 0, At, B0); PG8_MMA(1, 1, At, B1); PG8_BAR; PG8_SCHED;
;     ...
;         if constexpr (ALIGN_EPI) { if (wr == 0) PG8_BAR; }
	s_add_i32 s8, s40, s2
	v_lshl_add_u64 v[90:91], v[214:215], 0, s[46:47]
	s_mov_b32 m0, s8
	ds_read_b128 v[178:181], v177 offset:49152
	ds_read_b128 v[182:185], v177 offset:50176
	ds_read_b128 v[186:189], v177 offset:51200
	ds_read_b128 v[190:193], v177 offset:52224
	ds_read_b128 v[194:197], v177 offset:53248
	ds_read_b128 v[198:201], v177 offset:54272
	ds_read_b128 v[206:209], v177 offset:55296
	ds_read_b128 v[210:213], v177 offset:56320
	global_load_lds_dwordx4 v[90:91], off
	s_add_i32 m0, s8, 0x2000
	s_add_u32 s6, s6, 0x40080
	v_lshl_add_u64 v[90:91], v[216:217], 0, s[46:47]
	s_addc_u32 s7, s7, 0
	s_add_i32 s8, s41, s2
	global_load_lds_dwordx4 v[90:91], off
	s_mov_b32 m0, s8
	v_lshl_add_u64 v[90:91], s[6:7], 0, v[164:165]
	global_load_lds_dwordx4 v[90:91], off
	s_add_i32 m0, s8, 0x2000
	v_lshl_add_u64 v[90:91], s[6:7], 0, v[160:161]
	global_load_lds_dwordx4 v[90:91], off
	s_mov_b32 m0, s16
	v_lshl_add_u64 v[90:91], v[218:219], 0, s[46:47]
	global_load_lds_dwordx4 v[90:91], off
	s_mov_b32 m0, s17
	v_lshl_add_u64 v[90:91], v[220:221], 0, s[46:47]
	global_load_lds_dwordx4 v[90:91], off
	s_waitcnt vmcnt(8)
	s_waitcnt lgkmcnt(0)
	s_barrier
	s_setprio 1
	s_waitcnt lgkmcnt(0)
	v_mfma_f32_16x16x32_bf16 v[90:93], v[58:61], v[178:181], v[92:95]
	v_mfma_f32_16x16x32_bf16 v[86:89], v[66:69], v[178:181], v[86:89]
	v_mfma_f32_16x16x32_bf16 v[46:49], v[58:61], v[186:189], v[46:49]
	v_mfma_f32_16x16x32_bf16 v[42:45], v[66:69], v[186:189], v[42:45]
	v_mfma_f32_16x16x32_bf16 v[30:33], v[58:61], v[194:197], v[30:33]
	v_mfma_f32_16x16x32_bf16 v[26:29], v[66:69], v[194:197], v[26:29]
	v_mfma_f32_16x16x32_bf16 v[14:17], v[58:61], v[206:209], v[14:17]
	v_mfma_f32_16x16x32_bf16 v[10:13], v[66:69], v[206:209], v[10:13]
	v_mfma_f32_16x16x32_bf16 v[92:95], v[62:65], v[182:185], v[90:93]
	v_mfma_f32_16x16x32_bf16 v[88:91], v[70:73], v[182:185], v[86:89]
	v_mfma_f32_16x16x32_bf16 v[46:49], v[62:65], v[190:193], v[46:49]
	v_mfma_f32_16x16x32_bf16 v[42:45], v[70:73], v[190:193], v[42:45]
	v_mfma_f32_16x16x32_bf16 v[30:33], v[62:65], v[198:201], v[30:33]
	v_mfma_f32_16x16x32_bf16 v[26:29], v[70:73], v[198:201], v[26:29]
	v_mfma_f32_16x16x32_bf16 v[14:17], v[62:65], v[210:213], v[14:17]
	v_mfma_f32_16x16x32_bf16 v[10:13], v[70:73], v[210:213], v[10:13]
	s_setprio 0
	s_setprio 1
	v_mfma_f32_16x16x32_bf16 v[54:57], v[74:77], v[178:181], v[54:57]
	v_mfma_f32_16x16x32_bf16 v[50:53], v[82:85], v[178:181], v[50:53]
	v_mfma_f32_16x16x32_bf16 v[38:41], v[74:77], v[186:189], v[38:41]
	v_mfma_f32_16x16x32_bf16 v[34:37], v[82:85], v[186:189], v[34:37]
	v_mfma_f32_16x16x32_bf16 v[22:25], v[74:77], v[194:197], v[22:25]
	v_mfma_f32_16x16x32_bf16 v[18:21], v[82:85], v[194:197], v[18:21]
	v_mfma_f32_16x16x32_bf16 v[6:9], v[74:77], v[206:209], v[6:9]
	v_mfma_f32_16x16x32_bf16 v[2:5], v[82:85], v[206:209], v[2:5]
	v_mfma_f32_16x16x32_bf16 v[54:57], v[78:81], v[182:185], v[54:57]
	v_mfma_f32_16x16x32_bf16 v[50:53], v[172:175], v[182:185], v[50:53]
	v_mfma_f32_16x16x32_bf16 v[38:41], v[78:81], v[190:193], v[38:41]
	v_mfma_f32_16x16x32_bf16 v[34:37], v[172:175], v[190:193], v[34:37]
	v_mfma_f32_16x16x32_bf16 v[22:25], v[78:81], v[198:201], v[22:25]
	v_mfma_f32_16x16x32_bf16 v[18:21], v[172:175], v[198:201], v[18:21]
	v_mfma_f32_16x16x32_bf16 v[6:9], v[78:81], v[210:213], v[6:9]
	v_mfma_f32_16x16x32_bf16 v[2:5], v[172:175], v[210:213], v[2:5]
	s_setprio 0
	s_barrier
	s_add_i32 s39, s39, 2
	s_add_u32 s4, s4, 0x100
	s_addc_u32 s5, s5, 0
	s_add_u32 s31, s31, 0x100
	s_addc_u32 s38, s38, 0
	s_cmp_gt_u32 s39, 13
	s_cbranch_scc0 .LBB0_147
	s_and_b64 vcc, exec, s[24:25]
	s_cbranch_vccz .LBB0_150
	s_barrier

; #define PG8_STAGE(bufoff, gbase, voff) do { _Pragma("unroll") for (int _i = 0; _i < 2; ++_i) \
;         __builtin_amdgcn_global_load_lds((const unsigned*)((const char*)(gbase) + (voff)[_i]), (PG8_LAS unsigned*)(lds + (bufoff) + ldsw + _i * 8192), 16, 0, 0); } while (0)
; #define PG8_LDA(dst, b, h) do { _Pragma("unroll") for (int m = 0; m < 4; ++m) _Pragma("unroll") for (int k = 0; k < 2; ++k) dst[m][k] = *(const PG8_LAS bf16x8*)(lds + PG8_SA(b, h) + aoff + m * 2048 + k * 1024); } while (0)
; #define PG8_LDB(dst, b, h) do { _Pragma("unroll") for (int n = 0; n < 2; ++n) _Pragma("unroll") for (int k = 0; k < 2; ++k) dst[n][k] = *(const PG8_LAS bf16x8*)(lds + PG8_SB(b, h) + boff + n * 2048 + k * 1024); } while (0)
; #define PG8_MMA(ai, bj, At, Bt) do { __builtin_amdgcn_s_setprio(1); _Pragma("unroll") for (int m = 0; m < 4; ++m) _Pragma("unroll") for (int n = 0; n < 2; ++n) _Pragma("unroll") for (int k = 0; k < 2; ++k) \
;         acc[ai][bj][m][n] = __builtin_amdgcn_mfma_f32_16x16x32_bf16(Bt[n][k], At[m][k], acc[ai][bj][m][n], 0, 0, 0); __builtin_amdgcn_s_setprio(0); } while (0)
; #define PG8_WAIT_V(n) asm volatile("s_waitcnt vmcnt(" #n ")" ::: "memory")
; #define PG8_WAIT_L(n) asm volatile("s_waitcnt lgkmcnt(" #n ")" ::: "memory")
; #define PG8_BAR __builtin_amdgcn_s_barrier()
; #define PG8_SCHED __builtin_amdgcn_sched_barrier(0)
; template <class Epi, class Sched, bool ALIGN_EPI = false, bool SP2 = false>
; __device__ __forceinline__ void gemm_phase(PG8_LAS unsigned char* lds, const Gemm g, const Sched& S, const Epi& E) {
;     ...
;         for (int t = 0; t < nt; t += 2) {
;             const bool last = (t == nt - 2);
;             const char* a1 = cA + (size_t)(t + 1) * kstep;
;             const char* a2 = last ? nA : cA + (size_t)(t + 2) * kstep; const char* b2 = last ? nB : cB + (size_t)(t + 2) * kstep;
;             const char* a3 = a2 + kstep; const char* b3 = b2 + kstep;
;             if (last && has_next) S.a_ready(nxt);
;             if constexpr (SP2) {
;             PG8_LDB(B0, 0, 0); PG8_LDB(B1, 0, 1); PG8_SCHED; PG8_LDA(At, 0, 0); PG8_STAGE(PG8_SA(1, 1), a1 + hstep, voffA);
;             PG8_WAIT_V(8); PG8_WAIT_L(0); PG8_BAR; PG8_MMA(0, 0, At, B0); PG8_MMA(0, 1, At, B1); PG8_BAR; PG8_SCHED;
;             PG8_LDA(At, 0, 1); PG8_STAGE(PG8_SB(0, 0), b2, voffB); PG8_STAGE(PG8_SB(0, 1), b2 + hstep, voffB); PG8_STAGE(PG8_SA(0, 0), a2, voffA);
.LBB0_622:
	s_add_u32 s6, s4, 0xfffc0080
	s_addc_u32 s7, s5, -1
	s_cmp_eq_u32 s35, 12
	s_cselect_b32 s9, s10, s7
	s_cselect_b32 s8, s11, s6
	s_cselect_b32 s7, s19, s34
	s_cselect_b32 s6, s23, s25
	s_add_i32 s36, 0, 0x10000
	v_add_u32_e32 v0, s36, v176
	s_add_i32 s38, 0, 0x14000
	ds_read_b128 v[58:61], v0
	ds_read_b128 v[62:65], v0 offset:1024
	ds_read_b128 v[66:69], v0 offset:2048
	ds_read_b128 v[70:73], v0 offset:3072
	v_add_u32_e32 v0, s38, v176
	ds_read_b128 v[74:77], v0
	ds_read_b128 v[78:81], v0 offset:1024
	ds_read_b128 v[82:85], v0 offset:2048
	ds_read_b128 v[172:175], v0 offset:3072
	v_lshl_add_u64 v[86:87], s[4:5], 0, v[168:169]
	s_add_i32 m0, s12, 0xc000
	ds_read_b128 v[178:181], v177
	ds_read_b128 v[182:185], v177 offset:1024
	ds_read_b128 v[186:189], v177 offset:2048
	ds_read_b128 v[190:193], v177 offset:3072
	ds_read_b128 v[194:197], v177 offset:4096
	ds_read_b128 v[198:201], v177 offset:5120
	ds_read_b128 v[206:209], v177 offset:6144
	ds_read_b128 v[210:213], v177 offset:7168
	global_load_lds_dwordx4 v[86:87], off
	s_add_i32 m0, s12, 0xe000
	v_lshl_add_u64 v[86:87], s[4:5], 0, v[170:171]
	global_load_lds_dwordx4 v[86:87], off
	s_waitcnt vmcnt(8)
	s_waitcnt lgkmcnt(0)
	s_barrier
	s_setprio 1
	s_waitcnt lgkmcnt(0)
	v_mfma_f32_16x16x32_bf16 v[156:159], v[58:61], v[178:181], v[156:159]
	v_mfma_f32_16x16x32_bf16 v[152:155], v[66:69], v[178:181], v[152:155]
	v_mfma_f32_16x16x32_bf16 v[140:143], v[58:61], v[186:189], v[140:143]
	v_mfma_f32_16x16x32_bf16 v[136:139], v[66:69], v[186:189], v[136:139]
	v_mfma_f32_16x16x32_bf16 v[124:127], v[58:61], v[194:197], v[124:127]
	v_mfma_f32_16x16x32_bf16 v[120:123], v[66:69], v[194:197], v[120:123]
	v_mfma_f32_16x16x32_bf16 v[108:111], v[58:61], v[206:209], v[108:111]
	v_mfma_f32_16x16x32_bf16 v[104:107], v[66:69], v[206:209], v[104:107]
	v_mfma_f32_16x16x32_bf16 v[156:159], v[62:65], v[182:185], v[156:159]
	v_mfma_f32_16x16x32_bf16 v[152:155], v[70:73], v[182:185], v[152:155]
	v_mfma_f32_16x16x32_bf16 v[140:143], v[62:65], v[190:193], v[140:143]
	v_mfma_f32_16x16x32_bf16 v[136:139], v[70:73], v[190:193], v[136:139]
	v_mfma_f32_16x16x32_bf16 v[124:127], v[62:65], v[198:201], v[124:127]
	v_mfma_f32_16x16x32_bf16 v[120:123], v[70:73], v[198:201], v[120:123]
	v_mfma_f32_16x16x32_bf16 v[108:111], v[62:65], v[210:213], v[108:111]
	v_mfma_f32_16x16x32_bf16 v[104:107], v[70:73], v[210:213], v[104:107]
	s_setprio 0
	s_setprio 1
	v_mfma_f32_16x16x32_bf16 v[148:151], v[74:77], v[178:181], v[148:151]
	v_mfma_f32_16x16x32_bf16 v[144:147], v[82:85], v[178:181], v[144:147]
	v_mfma_f32_16x16x32_bf16 v[132:135], v[74:77], v[186:189], v[132:135]
	v_mfma_f32_16x16x32_bf16 v[128:131], v[82:85], v[186:189], v[128:131]
	v_mfma_f32_16x16x32_bf16 v[116:119], v[74:77], v[194:197], v[116:119]
	v_mfma_f32_16x16x32_bf16 v[112:115], v[82:85], v[194:197], v[112:115]
	v_mfma_f32_16x16x32_bf16 v[100:103], v[74:77], v[206:209], v[100:103]
	v_mfma_f32_16x16x32_bf16 v[96:99], v[82:85], v[206:209], v[96:99]
	v_mfma_f32_16x16x32_bf16 v[148:151], v[78:81], v[182:185], v[148:151]
	v_mfma_f32_16x16x32_bf16 v[144:147], v[172:175], v[182:185], v[144:147]
	v_mfma_f32_16x16x32_bf16 v[132:135], v[78:81], v[190:193], v[132:135]
	v_mfma_f32_16x16x32_bf16 v[128:131], v[172:175], v[190:193], v[128:131]
	v_mfma_f32_16x16x32_bf16 v[116:119], v[78:81], v[198:201], v[116:119]
	v_mfma_f32_16x16x32_bf16 v[112:115], v[172:175], v[198:201], v[112:115]
	v_mfma_f32_16x16x32_bf16 v[100:103], v[78:81], v[210:213], v[100:103]
	v_mfma_f32_16x16x32_bf16 v[96:99], v[172:175], v[210:213], v[96:99]
	s_setprio 0
	s_barrier
	s_add_i32 s36, s36, s2
	v_lshl_add_u64 v[214:215], s[6:7], 0, v[164:165]
	s_mov_b32 m0, s36
	ds_read_b128 v[178:181], v177 offset:16384
	ds_read_b128 v[182:185], v177 offset:17408
	ds_read_b128 v[186:189], v177 offset:18432
	ds_read_b128 v[190:193], v177 offset:19456
	ds_read_b128 v[194:197], v177 offset:20480
	ds_read_b128 v[198:201], v177 offset:21504
	ds_read_b128 v[206:209], v177 offset:22528
	ds_read_b128 v[210:213], v177 offset:23552
	global_load_lds_dwordx4 v[214:215], off
	s_add_i32 m0, s36, 0x2000
	s_add_u32 s36, s6, 0x40000
	v_lshl_add_u64 v[216:217], s[6:7], 0, v[160:161]
	s_addc_u32 s37, s7, 0
	s_add_i32 s38, s38, s2
	global_load_lds_dwordx4 v[216:217], off
	v_lshl_add_u64 v[86:87], s[36:37], 0, v[164:165]
	s_mov_b32 m0, s38
	v_lshl_add_u64 v[218:219], s[8:9], 0, v[166:167]
	global_load_lds_dwordx4 v[86:87], off
	v_lshl_add_u64 v[86:87], s[36:37], 0, v[160:161]
	s_add_i32 m0, s38, 0x2000
	v_lshl_add_u64 v[220:221], s[8:9], 0, v[162:163]
	global_load_lds_dwordx4 v[86:87], off
	s_mov_b32 m0, s12
	s_nop 0
	global_load_lds_dwordx4 v[218:219], off
	s_mov_b32 m0, s13
	s_nop 0
	global_load_lds_dwordx4 v[220:221], off
	s_waitcnt vmcnt(8)
	s_waitcnt lgkmcnt(0)
	s_barrier
; #define PG8_STAGE(bufoff, gbase, voff) do { _Pragma("unroll") for (int _i = 0; _i < 2; ++_i) \
;         __builtin_amdgcn_global_load_lds((const unsigned*)((const char*)(gbase) + (voff)[_i]), (PG8_LAS unsigned*)(lds + (bufoff) + ldsw + _i * 8192), 16, 0, 0); } while (0)
; #define PG8_LDA(dst, b, h) do { _Pragma("unroll") for (int m = 0; m < 4; ++m) _Pragma("unroll") for (int k = 0; k < 2; ++k) dst[m][k] = *(const PG8_LAS bf16x8*)(lds + PG8_SA(b, h) + aoff + m * 2048 + k * 1024); } while (0)
; #define PG8_LDB(dst, b, h) do { _Pragma("unroll") for (int n = 0; n < 2; ++n) _Pragma("unroll") for (int k = 0; k < 2; ++k) dst[n][k] = *(const PG8_LAS bf16x8*)(lds + PG8_SB(b, h) + boff + n * 2048 + k * 1024); } while (0)
; #define PG8_MMA(ai, bj, At, Bt) do { __builtin_amdgcn_s_setprio(1); _Pragma("unroll") for (int m = 0; m < 4; ++m) _Pragma("unroll") for (int n = 0; n < 2; ++n) _Pragma("unroll") for (int k = 0; k < 2; ++k) \
;         acc[ai][bj][m][n] = __builtin_amdgcn_mfma_f32_16x16x32_bf16(Bt[n][k], At[m][k], acc[ai][bj][m][n], 0, 0, 0); __builtin_amdgcn_s_setprio(0); } while (0)
; #define PG8_WAIT_V(n) asm volatile("s_waitcnt vmcnt(" #n ")" ::: "memory")
; #define PG8_WAIT_L(n) asm volatile("s_waitcnt lgkmcnt(" #n ")" ::: "memory")
; #define PG8_BAR __builtin_amdgcn_s_barrier()
; #define PG8_SCHED __builtin_amdgcn_sched_barrier(0)
; template <class Epi, class Sched, bool ALIGN_EPI = false, bool SP2 = false>
; __device__ __forceinline__ void gemm_phase(PG8_LAS unsigned char* lds, const Gemm g, const Sched& S, const Epi& E) {
;     ...
;             PG8_WAIT_V(8); PG8_WAIT_L(0); PG8_BAR; PG8_MMA(1, 0, At, B0); PG8_MMA(1, 1, At, B1); PG8_BAR; PG8_SCHED;
;             PG8_LDB(B0, 1, 0); PG8_LDB(B1, 1, 1); PG8_SCHED; PG8_LDA(At, 1, 0); PG8_STAGE(PG8_SA(0, 1), a2 + hstep, voffA);
;             PG8_WAIT_V(8); PG8_WAIT_L(0); PG8_BAR; PG8_MMA(0, 0, At, B0); PG8_MMA(0, 1, At, B1); PG8_BAR; PG8_SCHED;
	s_setprio 1
	s_waitcnt lgkmcnt(0)
	v_mfma_f32_16x16x32_bf16 v[92:95], v[58:61], v[178:181], v[92:95]
	v_mfma_f32_16x16x32_bf16 v[86:89], v[66:69], v[178:181], v[88:91]
	v_mfma_f32_16x16x32_bf16 v[46:49], v[58:61], v[186:189], v[46:49]
	v_mfma_f32_16x16x32_bf16 v[42:45], v[66:69], v[186:189], v[42:45]
	v_mfma_f32_16x16x32_bf16 v[30:33], v[58:61], v[194:197], v[30:33]
	v_mfma_f32_16x16x32_bf16 v[26:29], v[66:69], v[194:197], v[26:29]
	v_mfma_f32_16x16x32_bf16 v[14:17], v[58:61], v[206:209], v[14:17]
	v_mfma_f32_16x16x32_bf16 v[10:13], v[66:69], v[206:209], v[10:13]
	v_mfma_f32_16x16x32_bf16 v[92:95], v[62:65], v[182:185], v[92:95]
	v_mfma_f32_16x16x32_bf16 v[86:89], v[70:73], v[182:185], v[86:89]
	v_mfma_f32_16x16x32_bf16 v[46:49], v[62:65], v[190:193], v[46:49]
	v_mfma_f32_16x16x32_bf16 v[42:45], v[70:73], v[190:193], v[42:45]
	v_mfma_f32_16x16x32_bf16 v[30:33], v[62:65], v[198:201], v[30:33]
	v_mfma_f32_16x16x32_bf16 v[26:29], v[70:73], v[198:201], v[26:29]
	v_mfma_f32_16x16x32_bf16 v[14:17], v[62:65], v[210:213], v[14:17]
	v_mfma_f32_16x16x32_bf16 v[10:13], v[70:73], v[210:213], v[10:13]
	s_setprio 0
	s_setprio 1
	v_mfma_f32_16x16x32_bf16 v[54:57], v[74:77], v[178:181], v[54:57]
	v_mfma_f32_16x16x32_bf16 v[50:53], v[82:85], v[178:181], v[50:53]
	v_mfma_f32_16x16x32_bf16 v[38:41], v[74:77], v[186:189], v[38:41]
	v_mfma_f32_16x16x32_bf16 v[34:37], v[82:85], v[186:189], v[34:37]
	v_mfma_f32_16x16x32_bf16 v[22:25], v[74:77], v[194:197], v[22:25]
	v_mfma_f32_16x16x32_bf16 v[18:21], v[82:85], v[194:197], v[18:21]
	v_mfma_f32_16x16x32_bf16 v[6:9], v[74:77], v[206:209], v[6:9]
	v_mfma_f32_16x16x32_bf16 v[2:5], v[82:85], v[206:209], v[2:5]
	v_mfma_f32_16x16x32_bf16 v[54:57], v[78:81], v[182:185], v[54:57]
	v_mfma_f32_16x16x32_bf16 v[50:53], v[172:175], v[182:185], v[50:53]
	v_mfma_f32_16x16x32_bf16 v[38:41], v[78:81], v[190:193], v[38:41]
	v_mfma_f32_16x16x32_bf16 v[34:37], v[172:175], v[190:193], v[34:37]
	v_mfma_f32_16x16x32_bf16 v[22:25], v[78:81], v[198:201], v[22:25]
	v_mfma_f32_16x16x32_bf16 v[18:21], v[172:175], v[198:201], v[18:21]
	v_mfma_f32_16x16x32_bf16 v[6:9], v[78:81], v[210:213], v[6:9]
	v_mfma_f32_16x16x32_bf16 v[2:5], v[172:175], v[210:213], v[2:5]
	s_setprio 0
	s_barrier
	s_add_i32 s36, 0, 0x18000
	v_add_u32_e32 v0, s36, v176
	s_add_i32 s37, 0, 0x1c000
	ds_read_b128 v[58:61], v0
	ds_read_b128 v[62:65], v0 offset:1024
	ds_read_b128 v[66:69], v0 offset:2048
	ds_read_b128 v[70:73], v0 offset:3072
	v_add_u32_e32 v0, s37, v176
	ds_read_b128 v[74:77], v0
	ds_read_b128 v[78:81], v0 offset:1024
	ds_read_b128 v[82:85], v0 offset:2048
	ds_read_b128 v[172:175], v0 offset:3072
	s_add_u32 s8, s8, 0x40000
	s_addc_u32 s9, s9, 0
	s_mov_b32 m0, s14
	v_lshl_add_u64 v[90:91], s[8:9], 0, v[166:167]
	ds_read_b128 v[178:181], v177 offset:32768
	ds_read_b128 v[182:185], v177 offset:33792
	ds_read_b128 v[186:189], v177 offset:34816
	ds_read_b128 v[190:193], v177 offset:35840
	ds_read_b128 v[194:197], v177 offset:36864
	ds_read_b128 v[198:201], v177 offset:37888
	ds_read_b128 v[206:209], v177 offset:38912
	ds_read_b128 v[210:213], v177 offset:39936
	global_load_lds_dwordx4 v[90:91], off
	s_mov_b32 m0, s15
	v_lshl_add_u64 v[90:91], s[8:9], 0, v[162:163]
	global_load_lds_dwordx4 v[90:91], off
	s_waitcnt vmcnt(8)
	s_waitcnt lgkmcnt(0)
	s_barrier
	s_setprio 1
	s_waitcnt lgkmcnt(0)
	v_mfma_f32_16x16x32_bf16 v[156:159], v[58:61], v[178:181], v[156:159]
	v_mfma_f32_16x16x32_bf16 v[152:155], v[66:69], v[178:181], v[152:155]
	v_mfma_f32_16x16x32_bf16 v[140:143], v[58:61], v[186:189], v[140:143]
	v_mfma_f32_16x16x32_bf16 v[136:139], v[66:69], v[186:189], v[136:139]
	v_mfma_f32_16x16x32_bf16 v[124:127], v[58:61], v[194:197], v[124:127]
	v_mfma_f32_16x16x32_bf16 v[120:123], v[66:69], v[194:197], v[120:123]
	v_mfma_f32_16x16x32_bf16 v[108:111], v[58:61], v[206:209], v[108:111]
	v_mfma_f32_16x16x32_bf16 v[104:107], v[66:69], v[206:209], v[104:107]
	v_mfma_f32_16x16x32_bf16 v[156:159], v[62:65], v[182:185], v[156:159]
	v_mfma_f32_16x16x32_bf16 v[152:155], v[70:73], v[182:185], v[152:155]
	v_mfma_f32_16x16x32_bf16 v[140:143], v[62:65], v[190:193], v[140:143]
	v_mfma_f32_16x16x32_bf16 v[136:139], v[70:73], v[190:193], v[136:139]
	v_mfma_f32_16x16x32_bf16 v[124:127], v[62:65], v[198:201], v[124:127]
	v_mfma_f32_16x16x32_bf16 v[120:123], v[70:73], v[198:201], v[120:123]
	v_mfma_f32_16x16x32_bf16 v[108:111], v[62:65], v[210:213], v[108:111]
	v_mfma_f32_16x16x32_bf16 v[104:107], v[70:73], v[210:213], v[104:107]
	s_setprio 0
	s_setprio 1
	v_mfma_f32_16x16x32_bf16 v[148:151], v[74:77], v[178:181], v[148:151]
	v_mfma_f32_16x16x32_bf16 v[144:147], v[82:85], v[178:181], v[144:147]
	v_mfma_f32_16x16x32_bf16 v[132:135], v[74:77], v[186:189], v[132:135]
	v_mfma_f32_16x16x32_bf16 v[128:131], v[82:85], v[186:189], v[128:131]
	v_mfma_f32_16x16x32_bf16 v[116:119], v[74:77], v[194:197], v[116:119]
	v_mfma_f32_16x16x32_bf16 v[112:115], v[82:85], v[194:197], v[112:115]
	v_mfma_f32_16x16x32_bf16 v[100:103], v[74:77], v[206:209], v[100:103]
	v_mfma_f32_16x16x32_bf16 v[96:99], v[82:85], v[206:209], v[96:99]
	v_mfma_f32_16x16x32_bf16 v[148:151], v[78:81], v[182:185], v[148:151]
	v_mfma_f32_16x16x32_bf16 v[144:147], v[172:175], v[182:185], v[144:147]
	v_mfma_f32_16x16x32_bf16 v[132:135], v[78:81], v[190:193], v[132:135]
	v_mfma_f32_16x16x32_bf16 v[128:131], v[172:175], v[190:193], v[128:131]
	v_mfma_f32_16x16x32_bf16 v[116:119], v[78:81], v[198:201], v[116:119]
	v_mfma_f32_16x16x32_bf16 v[112:115], v[172:175], v[198:201], v[112:115]
	v_mfma_f32_16x16x32_bf16 v[100:103], v[78:81], v[210:213], v[100:103]
	v_mfma_f32_16x16x32_bf16 v[96:99], v[172:175], v[210:213], v[96:99]
	s_setprio 0
	s_barrier
; #define PG8_STAGE(bufoff, gbase, voff) do { _Pragma("unroll") for (int _i = 0; _i < 2; ++_i) \
;         __builtin_amdgcn_global_load_lds((const unsigned*)((const char*)(gbase) + (voff)[_i]), (PG8_LAS unsigned*)(lds + (bufoff) + ldsw + _i * 8192), 16, 0, 0); } while (0)
; #define PG8_LDA(dst, b, h) do { _Pragma("unroll") for (int m = 0; m < 4; ++m) _Pragma("unroll") for (int k = 0; k < 2; ++k) dst[m][k] = *(const PG8_LAS bf16x8*)(lds + PG8_SA(b, h) + aoff + m * 2048 + k * 1024); } while (0)
; #define PG8_MMA(ai, bj, At, Bt) do { __builtin_amdgcn_s_setprio(1); _Pragma("unroll") for (int m = 0; m < 4; ++m) _Pragma("unroll") for (int n = 0; n < 2; ++n) _Pragma("unroll") for (int k = 0; k < 2; ++k) \
;         acc[ai][bj][m][n] = __builtin_amdgcn_mfma_f32_16x16x32_bf16(Bt[n][k], At[m][k], acc[ai][bj][m][n], 0, 0, 0); __builtin_amdgcn_s_setprio(0); } while (0)
; #define PG8_WAIT_V(n) asm volatile("s_waitcnt vmcnt(" #n ")" ::: "memory")
; #define PG8_WAIT_L(n) asm volatile("s_waitcnt lgkmcnt(" #n ")" ::: "memory")
; #define PG8_BAR __builtin_amdgcn_s_barrier()
; #define PG8_SCHED __builtin_amdgcn_sched_barrier(0)
; template <class Epi, class Sched, bool ALIGN_EPI = false, bool SP2 = false>
; __device__ __forceinline__ void gemm_phase(PG8_LAS unsigned char* lds, const Gemm g, const Sched& S, const Epi& E) {
;     ...
;             PG8_LDA(At, 1, 1); PG8_STAGE(PG8_SB(1, 0), b3, voffB); PG8_STAGE(PG8_SB(1, 1), b3 + hstep, voffB); PG8_STAGE(PG8_SA(1, 0), a3, voffA);
;             PG8_WAIT_V(8); PG8_WAIT_L(0); PG8_BAR; PG8_MMA(1, 0, At, B0); PG8_MMA(1, 1, At, B1); PG8_BAR; PG8_SCHED;
;     ...
;         if constexpr (ALIGN_EPI) { if (wr == 0) PG8_BAR; }
	s_add_i32 s8, s36, s2
	v_lshl_add_u64 v[90:91], v[214:215], 0, s[40:41]
	s_mov_b32 m0, s8
	ds_read_b128 v[178:181], v177 offset:49152
	ds_read_b128 v[182:185], v177 offset:50176
	ds_read_b128 v[186:189], v177 offset:51200
	ds_read_b128 v[190:193], v177 offset:52224
	ds_read_b128 v[194:197], v177 offset:53248
	ds_read_b128 v[198:201], v177 offset:54272
	ds_read_b128 v[206:209], v177 offset:55296
	ds_read_b128 v[210:213], v177 offset:56320
	global_load_lds_dwordx4 v[90:91], off
	s_add_i32 m0, s8, 0x2000
	s_add_u32 s6, s6, 0x40080
	v_lshl_add_u64 v[90:91], v[216:217], 0, s[40:41]
	s_addc_u32 s7, s7, 0
	s_add_i32 s8, s37, s2
	global_load_lds_dwordx4 v[90:91], off
	s_mov_b32 m0, s8
	v_lshl_add_u64 v[90:91], s[6:7], 0, v[164:165]
	global_load_lds_dwordx4 v[90:91], off
	s_add_i32 m0, s8, 0x2000
	v_lshl_add_u64 v[90:91], s[6:7], 0, v[160:161]
	global_load_lds_dwordx4 v[90:91], off
	s_mov_b32 m0, s16
	v_lshl_add_u64 v[90:91], v[218:219], 0, s[40:41]
	global_load_lds_dwordx4 v[90:91], off
	s_mov_b32 m0, s17
	v_lshl_add_u64 v[90:91], v[220:221], 0, s[40:41]
	global_load_lds_dwordx4 v[90:91], off
	s_waitcnt vmcnt(8)
	s_waitcnt lgkmcnt(0)
	s_barrier
	s_setprio 1
	s_waitcnt lgkmcnt(0)
	v_mfma_f32_16x16x32_bf16 v[90:93], v[58:61], v[178:181], v[92:95]
	v_mfma_f32_16x16x32_bf16 v[86:89], v[66:69], v[178:181], v[86:89]
	v_mfma_f32_16x16x32_bf16 v[46:49], v[58:61], v[186:189], v[46:49]
	v_mfma_f32_16x16x32_bf16 v[42:45], v[66:69], v[186:189], v[42:45]
	v_mfma_f32_16x16x32_bf16 v[30:33], v[58:61], v[194:197], v[30:33]
	v_mfma_f32_16x16x32_bf16 v[26:29], v[66:69], v[194:197], v[26:29]
	v_mfma_f32_16x16x32_bf16 v[14:17], v[58:61], v[206:209], v[14:17]
	v_mfma_f32_16x16x32_bf16 v[10:13], v[66:69], v[206:209], v[10:13]
	v_mfma_f32_16x16x32_bf16 v[92:95], v[62:65], v[182:185], v[90:93]
	v_mfma_f32_16x16x32_bf16 v[88:91], v[70:73], v[182:185], v[86:89]
	v_mfma_f32_16x16x32_bf16 v[46:49], v[62:65], v[190:193], v[46:49]
	v_mfma_f32_16x16x32_bf16 v[42:45], v[70:73], v[190:193], v[42:45]
	v_mfma_f32_16x16x32_bf16 v[30:33], v[62:65], v[198:201], v[30:33]
	v_mfma_f32_16x16x32_bf16 v[26:29], v[70:73], v[198:201], v[26:29]
	v_mfma_f32_16x16x32_bf16 v[14:17], v[62:65], v[210:213], v[14:17]
	v_mfma_f32_16x16x32_bf16 v[10:13], v[70:73], v[210:213], v[10:13]
	s_setprio 0
	s_setprio 1
	v_mfma_f32_16x16x32_bf16 v[54:57], v[74:77], v[178:181], v[54:57]
	v_mfma_f32_16x16x32_bf16 v[50:53], v[82:85], v[178:181], v[50:53]
	v_mfma_f32_16x16x32_bf16 v[38:41], v[74:77], v[186:189], v[38:41]
	v_mfma_f32_16x16x32_bf16 v[34:37], v[82:85], v[186:189], v[34:37]
	v_mfma_f32_16x16x32_bf16 v[22:25], v[74:77], v[194:197], v[22:25]
	v_mfma_f32_16x16x32_bf16 v[18:21], v[82:85], v[194:197], v[18:21]
	v_mfma_f32_16x16x32_bf16 v[6:9], v[74:77], v[206:209], v[6:9]
	v_mfma_f32_16x16x32_bf16 v[2:5], v[82:85], v[206:209], v[2:5]
	v_mfma_f32_16x16x32_bf16 v[54:57], v[78:81], v[182:185], v[54:57]
	v_mfma_f32_16x16x32_bf16 v[50:53], v[172:175], v[182:185], v[50:53]
	v_mfma_f32_16x16x32_bf16 v[38:41], v[78:81], v[190:193], v[38:41]
	v_mfma_f32_16x16x32_bf16 v[34:37], v[172:175], v[190:193], v[34:37]
	v_mfma_f32_16x16x32_bf16 v[22:25], v[78:81], v[198:201], v[22:25]
	v_mfma_f32_16x16x32_bf16 v[18:21], v[172:175], v[198:201], v[18:21]
	v_mfma_f32_16x16x32_bf16 v[6:9], v[78:81], v[210:213], v[6:9]
	v_mfma_f32_16x16x32_bf16 v[2:5], v[172:175], v[210:213], v[2:5]
	s_setprio 0
	s_barrier
	s_add_i32 s35, s35, 2
	s_add_u32 s4, s4, 0x100
	s_addc_u32 s5, s5, 0
	s_add_u32 s25, s25, 0x100
	s_addc_u32 s34, s34, 0
	s_cmp_gt_u32 s35, 13
	s_cbranch_scc0 .LBB0_622
	s_and_b64 vcc, exec, s[20:21]
	s_cbranch_vccz .LBB0_625
	s_barrier

; #define PG8_STAGE(bufoff, gbase, voff) do { _Pragma("unroll") for (int _i = 0; _i < 2; ++_i) \
;         __builtin_amdgcn_global_load_lds((const unsigned*)((const char*)(gbase) + (voff)[_i]), (PG8_LAS unsigned*)(lds + (bufoff) + ldsw + _i * 8192), 16, 0, 0); } while (0)
; #define PG8_LDA(dst, b, h) do { _Pragma("unroll") for (int m = 0; m < 4; ++m) _Pragma("unroll") for (int k = 0; k < 2; ++k) dst[m][k] = *(const PG8_LAS bf16x8*)(lds + PG8_SA(b, h) + aoff + m * 2048 + k * 1024); } while (0)
; #define PG8_LDB(dst, b, h) do { _Pragma("unroll") for (int n = 0; n < 2; ++n) _Pragma("unroll") for (int k = 0; k < 2; ++k) dst[n][k] = *(const PG8_LAS bf16x8*)(lds + PG8_SB(b, h) + boff + n * 2048 + k * 1024); } while (0)
; #define PG8_MMA(ai, bj, At, Bt) do { __builtin_amdgcn_s_setprio(1); _Pragma("unroll") for (int m = 0; m < 4; ++m) _Pragma("unroll") for (int n = 0; n < 2; ++n) _Pragma("unroll") for (int k = 0; k < 2; ++k) \
;         acc[ai][bj][m][n] = __builtin_amdgcn_mfma_f32_16x16x32_bf16(Bt[n][k], At[m][k], acc[ai][bj][m][n], 0, 0, 0); __builtin_amdgcn_s_setprio(0); } while (0)
; #define PG8_WAIT_V(n) asm volatile("s_waitcnt vmcnt(" #n ")" ::: "memory")
; #define PG8_WAIT_L(n) asm volatile("s_waitcnt lgkmcnt(" #n ")" ::: "memory")
; #define PG8_BAR __builtin_amdgcn_s_barrier()
; #define PG8_SCHED __builtin_amdgcn_sched_barrier(0)
; template <class Epi, class Sched, bool ALIGN_EPI = false, bool SP2 = false>
; __device__ __forceinline__ void gemm_phase(PG8_LAS unsigned char* lds, const Gemm g, const Sched& S, const Epi& E) {
;     ...
;         for (int t = 0; t < nt; t += 2) {
;             const bool last = (t == nt - 2);
;             const char* a1 = cA + (size_t)(t + 1) * kstep;
;             const char* a2 = last ? nA : cA + (size_t)(t + 2) * kstep; const char* b2 = last ? nB : cB + (size_t)(t + 2) * kstep;
;             const char* a3 = a2 + kstep; const char* b3 = b2 + kstep;
;             if (last && has_next) S.a_ready(nxt);
;             if constexpr (SP2) {
;             PG8_LDB(B0, 0, 0); PG8_LDB(B1, 0, 1); PG8_SCHED; PG8_LDA(At, 0, 0); PG8_STAGE(PG8_SA(1, 1), a1 + hstep, voffA);
;             PG8_WAIT_V(8); PG8_WAIT_L(0); PG8_BAR; PG8_MMA(0, 0, At, B0); PG8_MMA(0, 1, At, B1); PG8_BAR; PG8_SCHED;
;             PG8_LDA(At, 0, 1); PG8_STAGE(PG8_SB(0, 0), b2, voffB); PG8_STAGE(PG8_SB(0, 1), b2 + hstep, voffB); PG8_STAGE(PG8_SA(0, 0), a2, voffA);
.LBB0_739:
	s_add_u32 s6, s4, 0xfffc0080
	s_addc_u32 s7, s5, -1
	s_cmp_eq_u32 s35, 12
	s_cselect_b32 s9, s11, s7
	s_cselect_b32 s8, s19, s6
	s_cselect_b32 s7, s23, s34
	s_cselect_b32 s6, s25, s31
	s_add_i32 s36, 0, 0x10000
	v_add_u32_e32 v0, s36, v176
	s_add_i32 s38, 0, 0x14000
	ds_read_b128 v[58:61], v0
	ds_read_b128 v[62:65], v0 offset:1024
	ds_read_b128 v[66:69], v0 offset:2048
	ds_read_b128 v[70:73], v0 offset:3072
	v_add_u32_e32 v0, s38, v176
	ds_read_b128 v[74:77], v0
	ds_read_b128 v[78:81], v0 offset:1024
	ds_read_b128 v[82:85], v0 offset:2048
	ds_read_b128 v[172:175], v0 offset:3072
	v_lshl_add_u64 v[86:87], s[4:5], 0, v[168:169]
	s_add_i32 m0, s12, 0xc000
	ds_read_b128 v[178:181], v177
	ds_read_b128 v[182:185], v177 offset:1024
	ds_read_b128 v[186:189], v177 offset:2048
	ds_read_b128 v[190:193], v177 offset:3072
	ds_read_b128 v[194:197], v177 offset:4096
	ds_read_b128 v[198:201], v177 offset:5120
	ds_read_b128 v[206:209], v177 offset:6144
	ds_read_b128 v[210:213], v177 offset:7168
	global_load_lds_dwordx4 v[86:87], off
	s_add_i32 m0, s12, 0xe000
	v_lshl_add_u64 v[86:87], s[4:5], 0, v[170:171]
	global_load_lds_dwordx4 v[86:87], off
	s_waitcnt vmcnt(8)
	s_waitcnt lgkmcnt(0)
	s_barrier
	s_setprio 1
	s_waitcnt lgkmcnt(0)
	v_mfma_f32_16x16x32_bf16 v[156:159], v[58:61], v[178:181], v[156:159]
	v_mfma_f32_16x16x32_bf16 v[152:155], v[66:69], v[178:181], v[152:155]
	v_mfma_f32_16x16x32_bf16 v[140:143], v[58:61], v[186:189], v[140:143]
	v_mfma_f32_16x16x32_bf16 v[136:139], v[66:69], v[186:189], v[136:139]
	v_mfma_f32_16x16x32_bf16 v[124:127], v[58:61], v[194:197], v[124:127]
	v_mfma_f32_16x16x32_bf16 v[120:123], v[66:69], v[194:197], v[120:123]
	v_mfma_f32_16x16x32_bf16 v[108:111], v[58:61], v[206:209], v[108:111]
	v_mfma_f32_16x16x32_bf16 v[104:107], v[66:69], v[206:209], v[104:107]
	v_mfma_f32_16x16x32_bf16 v[156:159], v[62:65], v[182:185], v[156:159]
	v_mfma_f32_16x16x32_bf16 v[152:155], v[70:73], v[182:185], v[152:155]
	v_mfma_f32_16x16x32_bf16 v[140:143], v[62:65], v[190:193], v[140:143]
	v_mfma_f32_16x16x32_bf16 v[136:139], v[70:73], v[190:193], v[136:139]
	v_mfma_f32_16x16x32_bf16 v[124:127], v[62:65], v[198:201], v[124:127]
	v_mfma_f32_16x16x32_bf16 v[120:123], v[70:73], v[198:201], v[120:123]
	v_mfma_f32_16x16x32_bf16 v[108:111], v[62:65], v[210:213], v[108:111]
	v_mfma_f32_16x16x32_bf16 v[104:107], v[70:73], v[210:213], v[104:107]
	s_setprio 0
	s_setprio 1
	v_mfma_f32_16x16x32_bf16 v[148:151], v[74:77], v[178:181], v[148:151]
	v_mfma_f32_16x16x32_bf16 v[144:147], v[82:85], v[178:181], v[144:147]
	v_mfma_f32_16x16x32_bf16 v[132:135], v[74:77], v[186:189], v[132:135]
	v_mfma_f32_16x16x32_bf16 v[128:131], v[82:85], v[186:189], v[128:131]
	v_mfma_f32_16x16x32_bf16 v[116:119], v[74:77], v[194:197], v[116:119]
	v_mfma_f32_16x16x32_bf16 v[112:115], v[82:85], v[194:197], v[112:115]
	v_mfma_f32_16x16x32_bf16 v[100:103], v[74:77], v[206:209], v[100:103]
	v_mfma_f32_16x16x32_bf16 v[96:99], v[82:85], v[206:209], v[96:99]
	v_mfma_f32_16x16x32_bf16 v[148:151], v[78:81], v[182:185], v[148:151]
	v_mfma_f32_16x16x32_bf16 v[144:147], v[172:175], v[182:185], v[144:147]
	v_mfma_f32_16x16x32_bf16 v[132:135], v[78:81], v[190:193], v[132:135]
	v_mfma_f32_16x16x32_bf16 v[128:131], v[172:175], v[190:193], v[128:131]
	v_mfma_f32_16x16x32_bf16 v[116:119], v[78:81], v[198:201], v[116:119]
	v_mfma_f32_16x16x32_bf16 v[112:115], v[172:175], v[198:201], v[112:115]
	v_mfma_f32_16x16x32_bf16 v[100:103], v[78:81], v[210:213], v[100:103]
	v_mfma_f32_16x16x32_bf16 v[96:99], v[172:175], v[210:213], v[96:99]
	s_setprio 0
	s_barrier
	s_add_i32 s36, s36, s2
	v_lshl_add_u64 v[214:215], s[6:7], 0, v[164:165]
	s_mov_b32 m0, s36
	ds_read_b128 v[178:181], v177 offset:16384
	ds_read_b128 v[182:185], v177 offset:17408
	ds_read_b128 v[186:189], v177 offset:18432
	ds_read_b128 v[190:193], v177 offset:19456
	ds_read_b128 v[194:197], v177 offset:20480
	ds_read_b128 v[198:201], v177 offset:21504
	ds_read_b128 v[206:209], v177 offset:22528
	ds_read_b128 v[210:213], v177 offset:23552
	global_load_lds_dwordx4 v[214:215], off
	s_add_i32 m0, s36, 0x2000
	s_add_u32 s36, s6, 0x40000
	v_lshl_add_u64 v[216:217], s[6:7], 0, v[160:161]
	s_addc_u32 s37, s7, 0
	s_add_i32 s38, s38, s2
	global_load_lds_dwordx4 v[216:217], off
	v_lshl_add_u64 v[86:87], s[36:37], 0, v[164:165]
	s_mov_b32 m0, s38
	v_lshl_add_u64 v[218:219], s[8:9], 0, v[166:167]
	global_load_lds_dwordx4 v[86:87], off
	v_lshl_add_u64 v[86:87], s[36:37], 0, v[160:161]
	s_add_i32 m0, s38, 0x2000
	v_lshl_add_u64 v[220:221], s[8:9], 0, v[162:163]
	global_load_lds_dwordx4 v[86:87], off
	s_mov_b32 m0, s12
	s_nop 0
	global_load_lds_dwordx4 v[218:219], off
	s_mov_b32 m0, s13
	s_nop 0
	global_load_lds_dwordx4 v[220:221], off
	s_waitcnt vmcnt(8)
	s_waitcnt lgkmcnt(0)
	s_barrier
; #define PG8_STAGE(bufoff, gbase, voff) do { _Pragma("unroll") for (int _i = 0; _i < 2; ++_i) \
;         __builtin_amdgcn_global_load_lds((const unsigned*)((const char*)(gbase) + (voff)[_i]), (PG8_LAS unsigned*)(lds + (bufoff) + ldsw + _i * 8192), 16, 0, 0); } while (0)
; #define PG8_LDA(dst, b, h) do { _Pragma("unroll") for (int m = 0; m < 4; ++m) _Pragma("unroll") for (int k = 0; k < 2; ++k) dst[m][k] = *(const PG8_LAS bf16x8*)(lds + PG8_SA(b, h) + aoff + m * 2048 + k * 1024); } while (0)
; #define PG8_LDB(dst, b, h) do { _Pragma("unroll") for (int n = 0; n < 2; ++n) _Pragma("unroll") for (int k = 0; k < 2; ++k) dst[n][k] = *(const PG8_LAS bf16x8*)(lds + PG8_SB(b, h) + boff + n * 2048 + k * 1024); } while (0)
; #define PG8_MMA(ai, bj, At, Bt) do { __builtin_amdgcn_s_setprio(1); _Pragma("unroll") for (int m = 0; m < 4; ++m) _Pragma("unroll") for (int n = 0; n < 2; ++n) _Pragma("unroll") for (int k = 0; k < 2; ++k) \
;         acc[ai][bj][m][n] = __builtin_amdgcn_mfma_f32_16x16x32_bf16(Bt[n][k], At[m][k], acc[ai][bj][m][n], 0, 0, 0); __builtin_amdgcn_s_setprio(0); } while (0)
; #define PG8_WAIT_V(n) asm volatile("s_waitcnt vmcnt(" #n ")" ::: "memory")
; #define PG8_WAIT_L(n) asm volatile("s_waitcnt lgkmcnt(" #n ")" ::: "memory")
; #define PG8_BAR __builtin_amdgcn_s_barrier()
; #define PG8_SCHED __builtin_amdgcn_sched_barrier(0)
; template <class Epi, class Sched, bool ALIGN_EPI = false, bool SP2 = false>
; __device__ __forceinline__ void gemm_phase(PG8_LAS unsigned char* lds, const Gemm g, const Sched& S, const Epi& E) {
;     ...
;             PG8_WAIT_V(8); PG8_WAIT_L(0); PG8_BAR; PG8_MMA(1, 0, At, B0); PG8_MMA(1, 1, At, B1); PG8_BAR; PG8_SCHED;
;             PG8_LDB(B0, 1, 0); PG8_LDB(B1, 1, 1); PG8_SCHED; PG8_LDA(At, 1, 0); PG8_STAGE(PG8_SA(0, 1), a2 + hstep, voffA);
;             PG8_WAIT_V(8); PG8_WAIT_L(0); PG8_BAR; PG8_MMA(0, 0, At, B0); PG8_MMA(0, 1, At, B1); PG8_BAR; PG8_SCHED;
	s_setprio 1
	s_waitcnt lgkmcnt(0)
	v_mfma_f32_16x16x32_bf16 v[92:95], v[58:61], v[178:181], v[92:95]
	v_mfma_f32_16x16x32_bf16 v[86:89], v[66:69], v[178:181], v[88:91]
	v_mfma_f32_16x16x32_bf16 v[46:49], v[58:61], v[186:189], v[46:49]
	v_mfma_f32_16x16x32_bf16 v[42:45], v[66:69], v[186:189], v[42:45]
	v_mfma_f32_16x16x32_bf16 v[30:33], v[58:61], v[194:197], v[30:33]
	v_mfma_f32_16x16x32_bf16 v[26:29], v[66:69], v[194:197], v[26:29]
	v_mfma_f32_16x16x32_bf16 v[14:17], v[58:61], v[206:209], v[14:17]
	v_mfma_f32_16x16x32_bf16 v[10:13], v[66:69], v[206:209], v[10:13]
	v_mfma_f32_16x16x32_bf16 v[92:95], v[62:65], v[182:185], v[92:95]
	v_mfma_f32_16x16x32_bf16 v[86:89], v[70:73], v[182:185], v[86:89]
	v_mfma_f32_16x16x32_bf16 v[46:49], v[62:65], v[190:193], v[46:49]
	v_mfma_f32_16x16x32_bf16 v[42:45], v[70:73], v[190:193], v[42:45]
	v_mfma_f32_16x16x32_bf16 v[30:33], v[62:65], v[198:201], v[30:33]
	v_mfma_f32_16x16x32_bf16 v[26:29], v[70:73], v[198:201], v[26:29]
	v_mfma_f32_16x16x32_bf16 v[14:17], v[62:65], v[210:213], v[14:17]
	v_mfma_f32_16x16x32_bf16 v[10:13], v[70:73], v[210:213], v[10:13]
	s_setprio 0
	s_setprio 1
	v_mfma_f32_16x16x32_bf16 v[54:57], v[74:77], v[178:181], v[54:57]
	v_mfma_f32_16x16x32_bf16 v[50:53], v[82:85], v[178:181], v[50:53]
	v_mfma_f32_16x16x32_bf16 v[38:41], v[74:77], v[186:189], v[38:41]
	v_mfma_f32_16x16x32_bf16 v[34:37], v[82:85], v[186:189], v[34:37]
	v_mfma_f32_16x16x32_bf16 v[22:25], v[74:77], v[194:197], v[22:25]
	v_mfma_f32_16x16x32_bf16 v[18:21], v[82:85], v[194:197], v[18:21]
	v_mfma_f32_16x16x32_bf16 v[6:9], v[74:77], v[206:209], v[6:9]
	v_mfma_f32_16x16x32_bf16 v[2:5], v[82:85], v[206:209], v[2:5]
	v_mfma_f32_16x16x32_bf16 v[54:57], v[78:81], v[182:185], v[54:57]
	v_mfma_f32_16x16x32_bf16 v[50:53], v[172:175], v[182:185], v[50:53]
	v_mfma_f32_16x16x32_bf16 v[38:41], v[78:81], v[190:193], v[38:41]
	v_mfma_f32_16x16x32_bf16 v[34:37], v[172:175], v[190:193], v[34:37]
	v_mfma_f32_16x16x32_bf16 v[22:25], v[78:81], v[198:201], v[22:25]
	v_mfma_f32_16x16x32_bf16 v[18:21], v[172:175], v[198:201], v[18:21]
	v_mfma_f32_16x16x32_bf16 v[6:9], v[78:81], v[210:213], v[6:9]
	v_mfma_f32_16x16x32_bf16 v[2:5], v[172:175], v[210:213], v[2:5]
	s_setprio 0
	s_barrier
	s_add_i32 s36, 0, 0x18000
	v_add_u32_e32 v0, s36, v176
	s_add_i32 s37, 0, 0x1c000
	ds_read_b128 v[58:61], v0
	ds_read_b128 v[62:65], v0 offset:1024
	ds_read_b128 v[66:69], v0 offset:2048
	ds_read_b128 v[70:73], v0 offset:3072
	v_add_u32_e32 v0, s37, v176
	ds_read_b128 v[74:77], v0
	ds_read_b128 v[78:81], v0 offset:1024
	ds_read_b128 v[82:85], v0 offset:2048
	ds_read_b128 v[172:175], v0 offset:3072
	s_add_u32 s8, s8, 0x40000
	s_addc_u32 s9, s9, 0
	s_mov_b32 m0, s14
	v_lshl_add_u64 v[90:91], s[8:9], 0, v[166:167]
	ds_read_b128 v[178:181], v177 offset:32768
	ds_read_b128 v[182:185], v177 offset:33792
	ds_read_b128 v[186:189], v177 offset:34816
	ds_read_b128 v[190:193], v177 offset:35840
	ds_read_b128 v[194:197], v177 offset:36864
	ds_read_b128 v[198:201], v177 offset:37888
	ds_read_b128 v[206:209], v177 offset:38912
	ds_read_b128 v[210:213], v177 offset:39936
	global_load_lds_dwordx4 v[90:91], off
	s_mov_b32 m0, s15
	v_lshl_add_u64 v[90:91], s[8:9], 0, v[162:163]
	global_load_lds_dwordx4 v[90:91], off
	s_waitcnt vmcnt(8)
	s_waitcnt lgkmcnt(0)
	s_barrier
	s_setprio 1
	s_waitcnt lgkmcnt(0)
	v_mfma_f32_16x16x32_bf16 v[156:159], v[58:61], v[178:181], v[156:159]
	v_mfma_f32_16x16x32_bf16 v[152:155], v[66:69], v[178:181], v[152:155]
	v_mfma_f32_16x16x32_bf16 v[140:143], v[58:61], v[186:189], v[140:143]
	v_mfma_f32_16x16x32_bf16 v[136:139], v[66:69], v[186:189], v[136:139]
	v_mfma_f32_16x16x32_bf16 v[124:127], v[58:61], v[194:197], v[124:127]
	v_mfma_f32_16x16x32_bf16 v[120:123], v[66:69], v[194:197], v[120:123]
	v_mfma_f32_16x16x32_bf16 v[108:111], v[58:61], v[206:209], v[108:111]
	v_mfma_f32_16x16x32_bf16 v[104:107], v[66:69], v[206:209], v[104:107]
	v_mfma_f32_16x16x32_bf16 v[156:159], v[62:65], v[182:185], v[156:159]
	v_mfma_f32_16x16x32_bf16 v[152:155], v[70:73], v[182:185], v[152:155]
	v_mfma_f32_16x16x32_bf16 v[140:143], v[62:65], v[190:193], v[140:143]
	v_mfma_f32_16x16x32_bf16 v[136:139], v[70:73], v[190:193], v[136:139]
	v_mfma_f32_16x16x32_bf16 v[124:127], v[62:65], v[198:201], v[124:127]
	v_mfma_f32_16x16x32_bf16 v[120:123], v[70:73], v[198:201], v[120:123]
	v_mfma_f32_16x16x32_bf16 v[108:111], v[62:65], v[210:213], v[108:111]
	v_mfma_f32_16x16x32_bf16 v[104:107], v[70:73], v[210:213], v[104:107]
	s_setprio 0
	s_setprio 1
	v_mfma_f32_16x16x32_bf16 v[148:151], v[74:77], v[178:181], v[148:151]
	v_mfma_f32_16x16x32_bf16 v[144:147], v[82:85], v[178:181], v[144:147]
	v_mfma_f32_16x16x32_bf16 v[132:135], v[74:77], v[186:189], v[132:135]
	v_mfma_f32_16x16x32_bf16 v[128:131], v[82:85], v[186:189], v[128:131]
	v_mfma_f32_16x16x32_bf16 v[116:119], v[74:77], v[194:197], v[116:119]
	v_mfma_f32_16x16x32_bf16 v[112:115], v[82:85], v[194:197], v[112:115]
	v_mfma_f32_16x16x32_bf16 v[100:103], v[74:77], v[206:209], v[100:103]
	v_mfma_f32_16x16x32_bf16 v[96:99], v[82:85], v[206:209], v[96:99]
	v_mfma_f32_16x16x32_bf16 v[148:151], v[78:81], v[182:185], v[148:151]
	v_mfma_f32_16x16x32_bf16 v[144:147], v[172:175], v[182:185], v[144:147]
	v_mfma_f32_16x16x32_bf16 v[132:135], v[78:81], v[190:193], v[132:135]
	v_mfma_f32_16x16x32_bf16 v[128:131], v[172:175], v[190:193], v[128:131]
	v_mfma_f32_16x16x32_bf16 v[116:119], v[78:81], v[198:201], v[116:119]
	v_mfma_f32_16x16x32_bf16 v[112:115], v[172:175], v[198:201], v[112:115]
	v_mfma_f32_16x16x32_bf16 v[100:103], v[78:81], v[210:213], v[100:103]
	v_mfma_f32_16x16x32_bf16 v[96:99], v[172:175], v[210:213], v[96:99]
	s_setprio 0
	s_barrier
; #define PG8_STAGE(bufoff, gbase, voff) do { _Pragma("unroll") for (int _i = 0; _i < 2; ++_i) \
;         __builtin_amdgcn_global_load_lds((const unsigned*)((const char*)(gbase) + (voff)[_i]), (PG8_LAS unsigned*)(lds + (bufoff) + ldsw + _i * 8192), 16, 0, 0); } while (0)
; #define PG8_LDA(dst, b, h) do { _Pragma("unroll") for (int m = 0; m < 4; ++m) _Pragma("unroll") for (int k = 0; k < 2; ++k) dst[m][k] = *(const PG8_LAS bf16x8*)(lds + PG8_SA(b, h) + aoff + m * 2048 + k * 1024); } while (0)
; #define PG8_MMA(ai, bj, At, Bt) do { __builtin_amdgcn_s_setprio(1); _Pragma("unroll") for (int m = 0; m < 4; ++m) _Pragma("unroll") for (int n = 0; n < 2; ++n) _Pragma("unroll") for (int k = 0; k < 2; ++k) \
;         acc[ai][bj][m][n] = __builtin_amdgcn_mfma_f32_16x16x32_bf16(Bt[n][k], At[m][k], acc[ai][bj][m][n], 0, 0, 0); __builtin_amdgcn_s_setprio(0); } while (0)
; #define PG8_WAIT_V(n) asm volatile("s_waitcnt vmcnt(" #n ")" ::: "memory")
; #define PG8_WAIT_L(n) asm volatile("s_waitcnt lgkmcnt(" #n ")" ::: "memory")
; #define PG8_BAR __builtin_amdgcn_s_barrier()
; #define PG8_SCHED __builtin_amdgcn_sched_barrier(0)
; template <class Epi, class Sched, bool ALIGN_EPI = false, bool SP2 = false>
; __device__ __forceinline__ void gemm_phase(PG8_LAS unsigned char* lds, const Gemm g, const Sched& S, const Epi& E) {
;     ...
;             PG8_LDA(At, 1, 1); PG8_STAGE(PG8_SB(1, 0), b3, voffB); PG8_STAGE(PG8_SB(1, 1), b3 + hstep, voffB); PG8_STAGE(PG8_SA(1, 0), a3, voffA);
;             PG8_WAIT_V(8); PG8_WAIT_L(0); PG8_BAR; PG8_MMA(1, 0, At, B0); PG8_MMA(1, 1, At, B1); PG8_BAR; PG8_SCHED;
;     ...
;         if constexpr (ALIGN_EPI) { if (wr == 0) PG8_BAR; }
	s_add_i32 s8, s36, s2
	v_lshl_add_u64 v[90:91], v[214:215], 0, s[40:41]
	s_mov_b32 m0, s8
	ds_read_b128 v[178:181], v177 offset:49152
	ds_read_b128 v[182:185], v177 offset:50176
	ds_read_b128 v[186:189], v177 offset:51200
	ds_read_b128 v[190:193], v177 offset:52224
	ds_read_b128 v[194:197], v177 offset:53248
	ds_read_b128 v[198:201], v177 offset:54272
	ds_read_b128 v[206:209], v177 offset:55296
	ds_read_b128 v[210:213], v177 offset:56320
	global_load_lds_dwordx4 v[90:91], off
	s_add_i32 m0, s8, 0x2000
	s_add_u32 s6, s6, 0x40080
	v_lshl_add_u64 v[90:91], v[216:217], 0, s[40:41]
	s_addc_u32 s7, s7, 0
	s_add_i32 s8, s37, s2
	global_load_lds_dwordx4 v[90:91], off
	s_mov_b32 m0, s8
	v_lshl_add_u64 v[90:91], s[6:7], 0, v[164:165]
	global_load_lds_dwordx4 v[90:91], off
	s_add_i32 m0, s8, 0x2000
	v_lshl_add_u64 v[90:91], s[6:7], 0, v[160:161]
	global_load_lds_dwordx4 v[90:91], off
	s_mov_b32 m0, s16
	v_lshl_add_u64 v[90:91], v[218:219], 0, s[40:41]
	global_load_lds_dwordx4 v[90:91], off
	s_mov_b32 m0, s17
	v_lshl_add_u64 v[90:91], v[220:221], 0, s[40:41]
	global_load_lds_dwordx4 v[90:91], off
	s_waitcnt vmcnt(8)
	s_waitcnt lgkmcnt(0)
	s_barrier
	s_setprio 1
	s_waitcnt lgkmcnt(0)
	v_mfma_f32_16x16x32_bf16 v[90:93], v[58:61], v[178:181], v[92:95]
	v_mfma_f32_16x16x32_bf16 v[86:89], v[66:69], v[178:181], v[86:89]
	v_mfma_f32_16x16x32_bf16 v[46:49], v[58:61], v[186:189], v[46:49]
	v_mfma_f32_16x16x32_bf16 v[42:45], v[66:69], v[186:189], v[42:45]
	v_mfma_f32_16x16x32_bf16 v[30:33], v[58:61], v[194:197], v[30:33]
	v_mfma_f32_16x16x32_bf16 v[26:29], v[66:69], v[194:197], v[26:29]
	v_mfma_f32_16x16x32_bf16 v[14:17], v[58:61], v[206:209], v[14:17]
	v_mfma_f32_16x16x32_bf16 v[10:13], v[66:69], v[206:209], v[10:13]
	v_mfma_f32_16x16x32_bf16 v[92:95], v[62:65], v[182:185], v[90:93]
	v_mfma_f32_16x16x32_bf16 v[88:91], v[70:73], v[182:185], v[86:89]
	v_mfma_f32_16x16x32_bf16 v[46:49], v[62:65], v[190:193], v[46:49]
	v_mfma_f32_16x16x32_bf16 v[42:45], v[70:73], v[190:193], v[42:45]
	v_mfma_f32_16x16x32_bf16 v[30:33], v[62:65], v[198:201], v[30:33]
	v_mfma_f32_16x16x32_bf16 v[26:29], v[70:73], v[198:201], v[26:29]
	v_mfma_f32_16x16x32_bf16 v[14:17], v[62:65], v[210:213], v[14:17]
	v_mfma_f32_16x16x32_bf16 v[10:13], v[70:73], v[210:213], v[10:13]
	s_setprio 0
	s_setprio 1
	v_mfma_f32_16x16x32_bf16 v[54:57], v[74:77], v[178:181], v[54:57]
	v_mfma_f32_16x16x32_bf16 v[50:53], v[82:85], v[178:181], v[50:53]
	v_mfma_f32_16x16x32_bf16 v[38:41], v[74:77], v[186:189], v[38:41]
	v_mfma_f32_16x16x32_bf16 v[34:37], v[82:85], v[186:189], v[34:37]
	v_mfma_f32_16x16x32_bf16 v[22:25], v[74:77], v[194:197], v[22:25]
	v_mfma_f32_16x16x32_bf16 v[18:21], v[82:85], v[194:197], v[18:21]
	v_mfma_f32_16x16x32_bf16 v[6:9], v[74:77], v[206:209], v[6:9]
	v_mfma_f32_16x16x32_bf16 v[2:5], v[82:85], v[206:209], v[2:5]
	v_mfma_f32_16x16x32_bf16 v[54:57], v[78:81], v[182:185], v[54:57]
	v_mfma_f32_16x16x32_bf16 v[50:53], v[172:175], v[182:185], v[50:53]
	v_mfma_f32_16x16x32_bf16 v[38:41], v[78:81], v[190:193], v[38:41]
	v_mfma_f32_16x16x32_bf16 v[34:37], v[172:175], v[190:193], v[34:37]
	v_mfma_f32_16x16x32_bf16 v[22:25], v[78:81], v[198:201], v[22:25]
	v_mfma_f32_16x16x32_bf16 v[18:21], v[172:175], v[198:201], v[18:21]
	v_mfma_f32_16x16x32_bf16 v[6:9], v[78:81], v[210:213], v[6:9]
	v_mfma_f32_16x16x32_bf16 v[2:5], v[172:175], v[210:213], v[2:5]
	s_setprio 0
	s_barrier
	s_add_i32 s35, s35, 2
	s_add_u32 s4, s4, 0x100
	s_addc_u32 s5, s5, 0
	s_add_u32 s31, s31, 0x100
	s_addc_u32 s34, s34, 0
	s_cmp_gt_u32 s35, 13
	s_cbranch_scc0 .LBB0_739
	s_and_b64 vcc, exec, s[20:21]
	s_cbranch_vccz .LBB0_742
	s_barrier

; #define PG8_STAGE(bufoff, gbase, voff) do { _Pragma("unroll") for (int _i = 0; _i < 2; ++_i) \
;         __builtin_amdgcn_global_load_lds((const unsigned*)((const char*)(gbase) + (voff)[_i]), (PG8_LAS unsigned*)(lds + (bufoff) + ldsw + _i * 8192), 16, 0, 0); } while (0)
; #define PG8_LDA(dst, b, h) do { _Pragma("unroll") for (int m = 0; m < 4; ++m) _Pragma("unroll") for (int k = 0; k < 2; ++k) dst[m][k] = *(const PG8_LAS bf16x8*)(lds + PG8_SA(b, h) + aoff + m * 2048 + k * 1024); } while (0)
; #define PG8_LDB(dst, b, h) do { _Pragma("unroll") for (int n = 0; n < 2; ++n) _Pragma("unroll") for (int k = 0; k < 2; ++k) dst[n][k] = *(const PG8_LAS bf16x8*)(lds + PG8_SB(b, h) + boff + n * 2048 + k * 1024); } while (0)
; #define PG8_MMA(ai, bj, At, Bt) do { __builtin_amdgcn_s_setprio(1); _Pragma("unroll") for (int m = 0; m < 4; ++m) _Pragma("unroll") for (int n = 0; n < 2; ++n) _Pragma("unroll") for (int k = 0; k < 2; ++k) \
;         acc[ai][bj][m][n] = __builtin_amdgcn_mfma_f32_16x16x32_bf16(Bt[n][k], At[m][k], acc[ai][bj][m][n], 0, 0, 0); __builtin_amdgcn_s_setprio(0); } while (0)
; #define PG8_WAIT_V(n) asm volatile("s_waitcnt vmcnt(" #n ")" ::: "memory")
; #define PG8_WAIT_L(n) asm volatile("s_waitcnt lgkmcnt(" #n ")" ::: "memory")
; #define PG8_BAR __builtin_amdgcn_s_barrier()
; #define PG8_SCHED __builtin_amdgcn_sched_barrier(0)
; template <class Epi, class Sched, bool ALIGN_EPI = false, bool SP2 = false>
; __device__ __forceinline__ void gemm_phase(PG8_LAS unsigned char* lds, const Gemm g, const Sched& S, const Epi& E) {
;     ...
;         for (int t = 0; t < nt; t += 2) {
;             const bool last = (t == nt - 2);
;             const char* a1 = cA + (size_t)(t + 1) * kstep;
;             const char* a2 = last ? nA : cA + (size_t)(t + 2) * kstep; const char* b2 = last ? nB : cB + (size_t)(t + 2) * kstep;
;             const char* a3 = a2 + kstep; const char* b3 = b2 + kstep;
;             if (last && has_next) S.a_ready(nxt);
;             if constexpr (SP2) {
;             PG8_LDB(B0, 0, 0); PG8_LDB(B1, 0, 1); PG8_SCHED; PG8_LDA(At, 0, 0); PG8_STAGE(PG8_SA(1, 1), a1 + hstep, voffA);
;             PG8_WAIT_V(8); PG8_WAIT_L(0); PG8_BAR; PG8_MMA(0, 0, At, B0); PG8_MMA(0, 1, At, B1); PG8_BAR; PG8_SCHED;
;             PG8_LDA(At, 0, 1); PG8_STAGE(PG8_SB(0, 0), b2, voffB); PG8_STAGE(PG8_SB(0, 1), b2 + hstep, voffB); PG8_STAGE(PG8_SA(0, 0), a2, voffA);
.LBB0_891:
	s_add_i32 s10, s6, 2
	s_add_u32 s11, s4, 0x80
	s_addc_u32 s7, s5, 0
	s_cmp_eq_u32 s62, s6
	s_cselect_b32 s7, s55, s7
	s_cselect_b32 s6, s54, s11
	s_cselect_b32 s45, s57, s9
	s_cselect_b32 s44, s56, s8
	s_add_i32 s11, 0, 0x10000
	v_add_u32_e32 v0, s11, v204
	s_add_i32 s46, 0, 0x14000
	ds_read_b128 v[130:133], v0
	ds_read_b128 v[134:137], v0 offset:1024
	ds_read_b128 v[138:141], v0 offset:2048
	ds_read_b128 v[142:145], v0 offset:3072
	v_add_u32_e32 v0, s46, v204
	ds_read_b128 v[146:149], v0
	ds_read_b128 v[150:153], v0 offset:1024
	ds_read_b128 v[154:157], v0 offset:2048
	ds_read_b128 v[158:161], v0 offset:3072
	v_lshl_add_u64 v[206:207], s[4:5], 0, v[210:211]
	s_add_i32 m0, s16, 0xc000
	ds_read_b128 v[162:165], v247
	ds_read_b128 v[166:169], v247 offset:1024
	ds_read_b128 v[170:173], v247 offset:2048
	ds_read_b128 v[174:177], v247 offset:3072
	ds_read_b128 v[178:181], v247 offset:4096
	ds_read_b128 v[182:185], v247 offset:5120
	ds_read_b128 v[186:189], v247 offset:6144
	ds_read_b128 v[190:193], v247 offset:7168
	global_load_lds_dwordx4 v[206:207], off
	s_add_i32 m0, s16, 0xe000
	v_lshl_add_u64 v[206:207], s[4:5], 0, v[212:213]
	global_load_lds_dwordx4 v[206:207], off
	s_waitcnt vmcnt(8)
	s_waitcnt lgkmcnt(0)
	s_barrier
	s_setprio 1
	s_waitcnt lgkmcnt(0)
	v_mfma_f32_16x16x32_bf16 v[122:125], v[130:133], v[162:165], v[122:125]
	v_mfma_f32_16x16x32_bf16 v[126:129], v[138:141], v[162:165], v[126:129]
	v_mfma_f32_16x16x32_bf16 v[106:109], v[130:133], v[170:173], v[106:109]
	v_mfma_f32_16x16x32_bf16 v[110:113], v[138:141], v[170:173], v[110:113]
	v_mfma_f32_16x16x32_bf16 v[90:93], v[130:133], v[178:181], v[90:93]
	v_mfma_f32_16x16x32_bf16 v[94:97], v[138:141], v[178:181], v[94:97]
	v_mfma_f32_16x16x32_bf16 v[74:77], v[130:133], v[186:189], v[74:77]
	v_mfma_f32_16x16x32_bf16 v[78:81], v[138:141], v[186:189], v[78:81]
	v_mfma_f32_16x16x32_bf16 v[122:125], v[134:137], v[166:169], v[122:125]
	v_mfma_f32_16x16x32_bf16 v[126:129], v[142:145], v[166:169], v[126:129]
	v_mfma_f32_16x16x32_bf16 v[106:109], v[134:137], v[174:177], v[106:109]
	v_mfma_f32_16x16x32_bf16 v[110:113], v[142:145], v[174:177], v[110:113]
	v_mfma_f32_16x16x32_bf16 v[90:93], v[134:137], v[182:185], v[90:93]
	v_mfma_f32_16x16x32_bf16 v[94:97], v[142:145], v[182:185], v[94:97]
	v_mfma_f32_16x16x32_bf16 v[74:77], v[134:137], v[190:193], v[74:77]
	v_mfma_f32_16x16x32_bf16 v[78:81], v[142:145], v[190:193], v[78:81]
	s_setprio 0
	s_setprio 1
	v_mfma_f32_16x16x32_bf16 v[114:117], v[146:149], v[162:165], v[114:117]
	v_mfma_f32_16x16x32_bf16 v[118:121], v[154:157], v[162:165], v[118:121]
	v_mfma_f32_16x16x32_bf16 v[98:101], v[146:149], v[170:173], v[98:101]
	v_mfma_f32_16x16x32_bf16 v[102:105], v[154:157], v[170:173], v[102:105]
	v_mfma_f32_16x16x32_bf16 v[82:85], v[146:149], v[178:181], v[82:85]
	v_mfma_f32_16x16x32_bf16 v[86:89], v[154:157], v[178:181], v[86:89]
	v_mfma_f32_16x16x32_bf16 v[66:69], v[146:149], v[186:189], v[66:69]
	v_mfma_f32_16x16x32_bf16 v[70:73], v[154:157], v[186:189], v[70:73]
	v_mfma_f32_16x16x32_bf16 v[114:117], v[150:153], v[166:169], v[114:117]
	v_mfma_f32_16x16x32_bf16 v[118:121], v[158:161], v[166:169], v[118:121]
	v_mfma_f32_16x16x32_bf16 v[98:101], v[150:153], v[174:177], v[98:101]
	v_mfma_f32_16x16x32_bf16 v[102:105], v[158:161], v[174:177], v[102:105]
	v_mfma_f32_16x16x32_bf16 v[82:85], v[150:153], v[182:185], v[82:85]
	v_mfma_f32_16x16x32_bf16 v[86:89], v[158:161], v[182:185], v[86:89]
	v_mfma_f32_16x16x32_bf16 v[66:69], v[150:153], v[190:193], v[66:69]
	v_mfma_f32_16x16x32_bf16 v[70:73], v[158:161], v[190:193], v[70:73]
	s_setprio 0
	s_barrier
	s_add_i32 s11, s11, s15
	v_lshl_add_u64 v[206:207], s[44:45], 0, v[196:197]
	s_mov_b32 m0, s11
	ds_read_b128 v[162:165], v247 offset:16384
	ds_read_b128 v[166:169], v247 offset:17408
	ds_read_b128 v[170:173], v247 offset:18432
	ds_read_b128 v[174:177], v247 offset:19456
	ds_read_b128 v[178:181], v247 offset:20480
	ds_read_b128 v[182:185], v247 offset:21504
	ds_read_b128 v[186:189], v247 offset:22528
	ds_read_b128 v[190:193], v247 offset:23552
	global_load_lds_dwordx4 v[206:207], off
	s_add_i32 m0, s11, 0x2000
	v_lshl_add_u64 v[208:209], s[44:45], 0, v[200:201]
	s_add_u32 s44, s44, s2
	s_addc_u32 s45, s45, 0
	s_add_i32 s11, s46, s15
	global_load_lds_dwordx4 v[208:209], off
	v_lshl_add_u64 v[214:215], s[44:45], 0, v[196:197]
	s_mov_b32 m0, s11
	v_lshl_add_u64 v[216:217], s[44:45], 0, v[200:201]
	global_load_lds_dwordx4 v[214:215], off
	s_add_i32 m0, s11, 0x2000
	v_lshl_add_u64 v[218:219], s[6:7], 0, v[194:195]
	global_load_lds_dwordx4 v[216:217], off
	s_mov_b32 m0, s16
	v_lshl_add_u64 v[220:221], s[6:7], 0, v[198:199]
	global_load_lds_dwordx4 v[218:219], off
	s_mov_b32 m0, s17
	s_nop 0
	global_load_lds_dwordx4 v[220:221], off
	s_waitcnt vmcnt(8)
	s_waitcnt lgkmcnt(0)
	s_barrier
; #define PG8_STAGE(bufoff, gbase, voff) do { _Pragma("unroll") for (int _i = 0; _i < 2; ++_i) \
;         __builtin_amdgcn_global_load_lds((const unsigned*)((const char*)(gbase) + (voff)[_i]), (PG8_LAS unsigned*)(lds + (bufoff) + ldsw + _i * 8192), 16, 0, 0); } while (0)
; #define PG8_LDA(dst, b, h) do { _Pragma("unroll") for (int m = 0; m < 4; ++m) _Pragma("unroll") for (int k = 0; k < 2; ++k) dst[m][k] = *(const PG8_LAS bf16x8*)(lds + PG8_SA(b, h) + aoff + m * 2048 + k * 1024); } while (0)
; #define PG8_LDB(dst, b, h) do { _Pragma("unroll") for (int n = 0; n < 2; ++n) _Pragma("unroll") for (int k = 0; k < 2; ++k) dst[n][k] = *(const PG8_LAS bf16x8*)(lds + PG8_SB(b, h) + boff + n * 2048 + k * 1024); } while (0)
; #define PG8_MMA(ai, bj, At, Bt) do { __builtin_amdgcn_s_setprio(1); _Pragma("unroll") for (int m = 0; m < 4; ++m) _Pragma("unroll") for (int n = 0; n < 2; ++n) _Pragma("unroll") for (int k = 0; k < 2; ++k) \
;         acc[ai][bj][m][n] = __builtin_amdgcn_mfma_f32_16x16x32_bf16(Bt[n][k], At[m][k], acc[ai][bj][m][n], 0, 0, 0); __builtin_amdgcn_s_setprio(0); } while (0)
; #define PG8_WAIT_V(n) asm volatile("s_waitcnt vmcnt(" #n ")" ::: "memory")
; #define PG8_WAIT_L(n) asm volatile("s_waitcnt lgkmcnt(" #n ")" ::: "memory")
; #define PG8_BAR __builtin_amdgcn_s_barrier()
; #define PG8_SCHED __builtin_amdgcn_sched_barrier(0)
; template <class Epi, class Sched, bool ALIGN_EPI = false, bool SP2 = false>
; __device__ __forceinline__ void gemm_phase(PG8_LAS unsigned char* lds, const Gemm g, const Sched& S, const Epi& E) {
;     ...
;             PG8_WAIT_V(8); PG8_WAIT_L(0); PG8_BAR; PG8_MMA(1, 0, At, B0); PG8_MMA(1, 1, At, B1); PG8_BAR; PG8_SCHED;
;             PG8_LDB(B0, 1, 0); PG8_LDB(B1, 1, 1); PG8_SCHED; PG8_LDA(At, 1, 0); PG8_STAGE(PG8_SA(0, 1), a2 + hstep, voffA);
;             PG8_WAIT_V(8); PG8_WAIT_L(0); PG8_BAR; PG8_MMA(0, 0, At, B0); PG8_MMA(0, 1, At, B1); PG8_BAR; PG8_SCHED;
	s_setprio 1
	s_waitcnt lgkmcnt(0)
	v_mfma_f32_16x16x32_bf16 v[58:61], v[130:133], v[162:165], v[58:61]
	v_mfma_f32_16x16x32_bf16 v[62:65], v[138:141], v[162:165], v[62:65]
	v_mfma_f32_16x16x32_bf16 v[42:45], v[130:133], v[170:173], v[42:45]
	v_mfma_f32_16x16x32_bf16 v[46:49], v[138:141], v[170:173], v[46:49]
	v_mfma_f32_16x16x32_bf16 v[26:29], v[130:133], v[178:181], v[26:29]
	v_mfma_f32_16x16x32_bf16 v[30:33], v[138:141], v[178:181], v[30:33]
	v_mfma_f32_16x16x32_bf16 v[10:13], v[130:133], v[186:189], v[10:13]
	v_mfma_f32_16x16x32_bf16 v[14:17], v[138:141], v[186:189], v[14:17]
	v_mfma_f32_16x16x32_bf16 v[58:61], v[134:137], v[166:169], v[58:61]
	v_mfma_f32_16x16x32_bf16 v[62:65], v[142:145], v[166:169], v[62:65]
	v_mfma_f32_16x16x32_bf16 v[42:45], v[134:137], v[174:177], v[42:45]
	v_mfma_f32_16x16x32_bf16 v[46:49], v[142:145], v[174:177], v[46:49]
	v_mfma_f32_16x16x32_bf16 v[26:29], v[134:137], v[182:185], v[26:29]
	v_mfma_f32_16x16x32_bf16 v[30:33], v[142:145], v[182:185], v[30:33]
	v_mfma_f32_16x16x32_bf16 v[10:13], v[134:137], v[190:193], v[10:13]
	v_mfma_f32_16x16x32_bf16 v[14:17], v[142:145], v[190:193], v[14:17]
	s_setprio 0
	s_setprio 1
	v_mfma_f32_16x16x32_bf16 v[50:53], v[146:149], v[162:165], v[50:53]
	v_mfma_f32_16x16x32_bf16 v[54:57], v[154:157], v[162:165], v[54:57]
	v_mfma_f32_16x16x32_bf16 v[34:37], v[146:149], v[170:173], v[34:37]
	v_mfma_f32_16x16x32_bf16 v[38:41], v[154:157], v[170:173], v[38:41]
	v_mfma_f32_16x16x32_bf16 v[18:21], v[146:149], v[178:181], v[18:21]
	v_mfma_f32_16x16x32_bf16 v[22:25], v[154:157], v[178:181], v[22:25]
	v_mfma_f32_16x16x32_bf16 v[2:5], v[146:149], v[186:189], v[2:5]
	v_mfma_f32_16x16x32_bf16 v[6:9], v[154:157], v[186:189], v[6:9]
	v_mfma_f32_16x16x32_bf16 v[50:53], v[150:153], v[166:169], v[50:53]
	v_mfma_f32_16x16x32_bf16 v[54:57], v[158:161], v[166:169], v[54:57]
	v_mfma_f32_16x16x32_bf16 v[34:37], v[150:153], v[174:177], v[34:37]
	v_mfma_f32_16x16x32_bf16 v[38:41], v[158:161], v[174:177], v[38:41]
	v_mfma_f32_16x16x32_bf16 v[18:21], v[150:153], v[182:185], v[18:21]
	v_mfma_f32_16x16x32_bf16 v[22:25], v[158:161], v[182:185], v[22:25]
	v_mfma_f32_16x16x32_bf16 v[2:5], v[150:153], v[190:193], v[2:5]
	v_mfma_f32_16x16x32_bf16 v[6:9], v[158:161], v[190:193], v[6:9]
	s_setprio 0
	s_barrier
	s_add_i32 s11, 0, 0x18000
	v_add_u32_e32 v0, s11, v204
	s_add_i32 s44, 0, 0x1c000
	ds_read_b128 v[130:133], v0
	ds_read_b128 v[134:137], v0 offset:1024
	ds_read_b128 v[138:141], v0 offset:2048
	ds_read_b128 v[142:145], v0 offset:3072
	v_add_u32_e32 v0, s44, v204
	ds_read_b128 v[146:149], v0
	ds_read_b128 v[150:153], v0 offset:1024
	ds_read_b128 v[154:157], v0 offset:2048
	ds_read_b128 v[158:161], v0 offset:3072
	s_add_u32 s6, s6, s2
	s_addc_u32 s7, s7, 0
	s_mov_b32 m0, s18
	v_lshl_add_u64 v[222:223], s[6:7], 0, v[194:195]
	ds_read_b128 v[162:165], v247 offset:32768
	ds_read_b128 v[166:169], v247 offset:33792
	ds_read_b128 v[170:173], v247 offset:34816
	ds_read_b128 v[174:177], v247 offset:35840
	ds_read_b128 v[178:181], v247 offset:36864
	ds_read_b128 v[182:185], v247 offset:37888
	ds_read_b128 v[186:189], v247 offset:38912
	ds_read_b128 v[190:193], v247 offset:39936
	global_load_lds_dwordx4 v[222:223], off
	s_mov_b32 m0, s19
	v_lshl_add_u64 v[222:223], s[6:7], 0, v[198:199]
	global_load_lds_dwordx4 v[222:223], off
	s_waitcnt vmcnt(8)
	s_waitcnt lgkmcnt(0)
	s_barrier
	s_setprio 1
	s_waitcnt lgkmcnt(0)
	v_mfma_f32_16x16x32_bf16 v[122:125], v[130:133], v[162:165], v[122:125]
	v_mfma_f32_16x16x32_bf16 v[126:129], v[138:141], v[162:165], v[126:129]
	v_mfma_f32_16x16x32_bf16 v[106:109], v[130:133], v[170:173], v[106:109]
	v_mfma_f32_16x16x32_bf16 v[110:113], v[138:141], v[170:173], v[110:113]
	v_mfma_f32_16x16x32_bf16 v[90:93], v[130:133], v[178:181], v[90:93]
	v_mfma_f32_16x16x32_bf16 v[94:97], v[138:141], v[178:181], v[94:97]
	v_mfma_f32_16x16x32_bf16 v[74:77], v[130:133], v[186:189], v[74:77]
	v_mfma_f32_16x16x32_bf16 v[78:81], v[138:141], v[186:189], v[78:81]
	v_mfma_f32_16x16x32_bf16 v[122:125], v[134:137], v[166:169], v[122:125]
	v_mfma_f32_16x16x32_bf16 v[126:129], v[142:145], v[166:169], v[126:129]
	v_mfma_f32_16x16x32_bf16 v[106:109], v[134:137], v[174:177], v[106:109]
	v_mfma_f32_16x16x32_bf16 v[110:113], v[142:145], v[174:177], v[110:113]
	v_mfma_f32_16x16x32_bf16 v[90:93], v[134:137], v[182:185], v[90:93]
	v_mfma_f32_16x16x32_bf16 v[94:97], v[142:145], v[182:185], v[94:97]
	v_mfma_f32_16x16x32_bf16 v[74:77], v[134:137], v[190:193], v[74:77]
	v_mfma_f32_16x16x32_bf16 v[78:81], v[142:145], v[190:193], v[78:81]
	s_setprio 0
	s_setprio 1
	v_mfma_f32_16x16x32_bf16 v[114:117], v[146:149], v[162:165], v[114:117]
	v_mfma_f32_16x16x32_bf16 v[118:121], v[154:157], v[162:165], v[118:121]
	v_mfma_f32_16x16x32_bf16 v[98:101], v[146:149], v[170:173], v[98:101]
	v_mfma_f32_16x16x32_bf16 v[102:105], v[154:157], v[170:173], v[102:105]
	v_mfma_f32_16x16x32_bf16 v[82:85], v[146:149], v[178:181], v[82:85]
	v_mfma_f32_16x16x32_bf16 v[86:89], v[154:157], v[178:181], v[86:89]
	v_mfma_f32_16x16x32_bf16 v[66:69], v[146:149], v[186:189], v[66:69]
	v_mfma_f32_16x16x32_bf16 v[70:73], v[154:157], v[186:189], v[70:73]
	v_mfma_f32_16x16x32_bf16 v[114:117], v[150:153], v[166:169], v[114:117]
	v_mfma_f32_16x16x32_bf16 v[118:121], v[158:161], v[166:169], v[118:121]
	v_mfma_f32_16x16x32_bf16 v[98:101], v[150:153], v[174:177], v[98:101]
	v_mfma_f32_16x16x32_bf16 v[102:105], v[158:161], v[174:177], v[102:105]
	v_mfma_f32_16x16x32_bf16 v[82:85], v[150:153], v[182:185], v[82:85]
	v_mfma_f32_16x16x32_bf16 v[86:89], v[158:161], v[182:185], v[86:89]
	v_mfma_f32_16x16x32_bf16 v[66:69], v[150:153], v[190:193], v[66:69]
	v_mfma_f32_16x16x32_bf16 v[70:73], v[158:161], v[190:193], v[70:73]
	s_setprio 0
	s_barrier
; #define PG8_STAGE(bufoff, gbase, voff) do { _Pragma("unroll") for (int _i = 0; _i < 2; ++_i) \
;         __builtin_amdgcn_global_load_lds((const unsigned*)((const char*)(gbase) + (voff)[_i]), (PG8_LAS unsigned*)(lds + (bufoff) + ldsw + _i * 8192), 16, 0, 0); } while (0)
; #define PG8_LDA(dst, b, h) do { _Pragma("unroll") for (int m = 0; m < 4; ++m) _Pragma("unroll") for (int k = 0; k < 2; ++k) dst[m][k] = *(const PG8_LAS bf16x8*)(lds + PG8_SA(b, h) + aoff + m * 2048 + k * 1024); } while (0)
; #define PG8_MMA(ai, bj, At, Bt) do { __builtin_amdgcn_s_setprio(1); _Pragma("unroll") for (int m = 0; m < 4; ++m) _Pragma("unroll") for (int n = 0; n < 2; ++n) _Pragma("unroll") for (int k = 0; k < 2; ++k) \
;         acc[ai][bj][m][n] = __builtin_amdgcn_mfma_f32_16x16x32_bf16(Bt[n][k], At[m][k], acc[ai][bj][m][n], 0, 0, 0); __builtin_amdgcn_s_setprio(0); } while (0)
; #define PG8_WAIT_V(n) asm volatile("s_waitcnt vmcnt(" #n ")" ::: "memory")
; #define PG8_WAIT_L(n) asm volatile("s_waitcnt lgkmcnt(" #n ")" ::: "memory")
; #define PG8_BAR __builtin_amdgcn_s_barrier()
; #define PG8_SCHED __builtin_amdgcn_sched_barrier(0)
; template <class Epi, class Sched, bool ALIGN_EPI = false, bool SP2 = false>
; __device__ __forceinline__ void gemm_phase(PG8_LAS unsigned char* lds, const Gemm g, const Sched& S, const Epi& E) {
;     ...
;             PG8_LDA(At, 1, 1); PG8_STAGE(PG8_SB(1, 0), b3, voffB); PG8_STAGE(PG8_SB(1, 1), b3 + hstep, voffB); PG8_STAGE(PG8_SA(1, 0), a3, voffA);
;             PG8_WAIT_V(8); PG8_WAIT_L(0); PG8_BAR; PG8_MMA(1, 0, At, B0); PG8_MMA(1, 1, At, B1); PG8_BAR; PG8_SCHED;
;     ...
;         if constexpr (ALIGN_EPI) { if (wr == 0) PG8_BAR; }
	s_add_i32 s6, s11, s15
	v_lshl_add_u64 v[206:207], v[206:207], 0, s[50:51]
	s_mov_b32 m0, s6
	ds_read_b128 v[162:165], v247 offset:49152
	ds_read_b128 v[166:169], v247 offset:50176
	ds_read_b128 v[170:173], v247 offset:51200
	ds_read_b128 v[174:177], v247 offset:52224
	ds_read_b128 v[178:181], v247 offset:53248
	ds_read_b128 v[182:185], v247 offset:54272
	ds_read_b128 v[186:189], v247 offset:55296
	ds_read_b128 v[190:193], v247 offset:56320
	global_load_lds_dwordx4 v[206:207], off
	v_lshl_add_u64 v[206:207], v[208:209], 0, s[50:51]
	s_add_i32 m0, s6, 0x2000
	s_add_i32 s6, s44, s15
	global_load_lds_dwordx4 v[206:207], off
	s_mov_b32 m0, s6
	v_lshl_add_u64 v[206:207], v[214:215], 0, s[50:51]
	global_load_lds_dwordx4 v[206:207], off
	s_add_i32 m0, s6, 0x2000
	v_lshl_add_u64 v[206:207], v[216:217], 0, s[50:51]
	global_load_lds_dwordx4 v[206:207], off
	s_mov_b32 m0, s31
	v_lshl_add_u64 v[206:207], v[218:219], 0, s[50:51]
	global_load_lds_dwordx4 v[206:207], off
	s_mov_b32 m0, s60
	v_lshl_add_u64 v[206:207], v[220:221], 0, s[50:51]
	global_load_lds_dwordx4 v[206:207], off
	s_waitcnt vmcnt(8)
	s_waitcnt lgkmcnt(0)
	s_barrier
	s_setprio 1
	s_waitcnt lgkmcnt(0)
	v_mfma_f32_16x16x32_bf16 v[58:61], v[130:133], v[162:165], v[58:61]
	v_mfma_f32_16x16x32_bf16 v[62:65], v[138:141], v[162:165], v[62:65]
	v_mfma_f32_16x16x32_bf16 v[42:45], v[130:133], v[170:173], v[42:45]
	v_mfma_f32_16x16x32_bf16 v[46:49], v[138:141], v[170:173], v[46:49]
	v_mfma_f32_16x16x32_bf16 v[26:29], v[130:133], v[178:181], v[26:29]
	v_mfma_f32_16x16x32_bf16 v[30:33], v[138:141], v[178:181], v[30:33]
	v_mfma_f32_16x16x32_bf16 v[10:13], v[130:133], v[186:189], v[10:13]
	v_mfma_f32_16x16x32_bf16 v[14:17], v[138:141], v[186:189], v[14:17]
	v_mfma_f32_16x16x32_bf16 v[58:61], v[134:137], v[166:169], v[58:61]
	v_mfma_f32_16x16x32_bf16 v[62:65], v[142:145], v[166:169], v[62:65]
	v_mfma_f32_16x16x32_bf16 v[42:45], v[134:137], v[174:177], v[42:45]
	v_mfma_f32_16x16x32_bf16 v[46:49], v[142:145], v[174:177], v[46:49]
	v_mfma_f32_16x16x32_bf16 v[26:29], v[134:137], v[182:185], v[26:29]
	v_mfma_f32_16x16x32_bf16 v[30:33], v[142:145], v[182:185], v[30:33]
	v_mfma_f32_16x16x32_bf16 v[10:13], v[134:137], v[190:193], v[10:13]
	v_mfma_f32_16x16x32_bf16 v[14:17], v[142:145], v[190:193], v[14:17]
	s_setprio 0
	s_setprio 1
	v_mfma_f32_16x16x32_bf16 v[50:53], v[146:149], v[162:165], v[50:53]
	v_mfma_f32_16x16x32_bf16 v[54:57], v[154:157], v[162:165], v[54:57]
	v_mfma_f32_16x16x32_bf16 v[34:37], v[146:149], v[170:173], v[34:37]
	v_mfma_f32_16x16x32_bf16 v[38:41], v[154:157], v[170:173], v[38:41]
	v_mfma_f32_16x16x32_bf16 v[18:21], v[146:149], v[178:181], v[18:21]
	v_mfma_f32_16x16x32_bf16 v[22:25], v[154:157], v[178:181], v[22:25]
	v_mfma_f32_16x16x32_bf16 v[2:5], v[146:149], v[186:189], v[2:5]
	v_mfma_f32_16x16x32_bf16 v[6:9], v[154:157], v[186:189], v[6:9]
	v_mfma_f32_16x16x32_bf16 v[50:53], v[150:153], v[166:169], v[50:53]
	v_mfma_f32_16x16x32_bf16 v[54:57], v[158:161], v[166:169], v[54:57]
	v_mfma_f32_16x16x32_bf16 v[34:37], v[150:153], v[174:177], v[34:37]
	v_mfma_f32_16x16x32_bf16 v[38:41], v[158:161], v[174:177], v[38:41]
	v_mfma_f32_16x16x32_bf16 v[18:21], v[150:153], v[182:185], v[18:21]
	v_mfma_f32_16x16x32_bf16 v[22:25], v[158:161], v[182:185], v[22:25]
	v_mfma_f32_16x16x32_bf16 v[2:5], v[150:153], v[190:193], v[2:5]
	v_mfma_f32_16x16x32_bf16 v[6:9], v[158:161], v[190:193], v[6:9]
	s_setprio 0
	s_barrier
	s_add_u32 s4, s4, 0x100
	s_addc_u32 s5, s5, 0
	s_add_u32 s8, s8, 0x100
	s_addc_u32 s9, s9, 0
	s_cmp_ge_u32 s10, s61
	s_mov_b32 s6, s10
	s_cbranch_scc0 .LBB0_891
	s_and_b64 vcc, exec, s[28:29]
	s_cbranch_vccz .LBB0_894
	s_barrier

; #define PG8_STAGE(bufoff, gbase, voff) do { _Pragma("unroll") for (int _i = 0; _i < 2; ++_i) \
;         __builtin_amdgcn_global_load_lds((const unsigned*)((const char*)(gbase) + (voff)[_i]), (PG8_LAS unsigned*)(lds + (bufoff) + ldsw + _i * 8192), 16, 0, 0); } while (0)
; #define PG8_LDA(dst, b, h) do { _Pragma("unroll") for (int m = 0; m < 4; ++m) _Pragma("unroll") for (int k = 0; k < 2; ++k) dst[m][k] = *(const PG8_LAS bf16x8*)(lds + PG8_SA(b, h) + aoff + m * 2048 + k * 1024); } while (0)
; #define PG8_LDB(dst, b, h) do { _Pragma("unroll") for (int n = 0; n < 2; ++n) _Pragma("unroll") for (int k = 0; k < 2; ++k) dst[n][k] = *(const PG8_LAS bf16x8*)(lds + PG8_SB(b, h) + boff + n * 2048 + k * 1024); } while (0)
; #define PG8_MMA(ai, bj, At, Bt) do { __builtin_amdgcn_s_setprio(1); _Pragma("unroll") for (int m = 0; m < 4; ++m) _Pragma("unroll") for (int n = 0; n < 2; ++n) _Pragma("unroll") for (int k = 0; k < 2; ++k) \
;         acc[ai][bj][m][n] = __builtin_amdgcn_mfma_f32_16x16x32_bf16(Bt[n][k], At[m][k], acc[ai][bj][m][n], 0, 0, 0); __builtin_amdgcn_s_setprio(0); } while (0)
; #define PG8_WAIT_V(n) asm volatile("s_waitcnt vmcnt(" #n ")" ::: "memory")
; #define PG8_BAR __builtin_amdgcn_s_barrier()
; template <class Epi, class Sched, bool ALIGN_EPI = false, bool SP2 = false>
; __device__ __forceinline__ void gemm_phase(PG8_LAS unsigned char* lds, const Gemm g, const Sched& S, const Epi& E) {
;     ...
;         for (int t = 0; t < nt; t += 2) {
;             const bool last = (t == nt - 2);
;             const char* a1 = cA + (size_t)(t + 1) * kstep;
;             const char* a2 = last ? nA : cA + (size_t)(t + 2) * kstep; const char* b2 = last ? nB : cB + (size_t)(t + 2) * kstep;
;             const char* a3 = a2 + kstep; const char* b3 = b2 + kstep;
;             if (last && has_next) S.a_ready(nxt);
;             if constexpr (SP2) {
;             PG8_LDB(B0, 0, 0); PG8_LDB(B1, 0, 1); PG8_SCHED; PG8_LDA(At, 0, 0); PG8_STAGE(PG8_SA(1, 1), a1 + hstep, voffA);
;             PG8_WAIT_V(8); PG8_WAIT_L(0); PG8_BAR; PG8_MMA(0, 0, At, B0); PG8_MMA(0, 1, At, B1); PG8_BAR; PG8_SCHED;
;             PG8_LDA(At, 0, 1); PG8_STAGE(PG8_SB(0, 0), b2, voffB); PG8_STAGE(PG8_SB(0, 1), b2 + hstep, voffB); PG8_STAGE(PG8_SA(0, 0), a2, voffA);
;             PG8_WAIT_V(8); PG8_WAIT_L(0); PG8_BAR; PG8_MMA(1, 0, At, B0); PG8_MMA(1, 1, At, B1); PG8_BAR; PG8_SCHED;
.LBB0_1239:
	s_or_b32 s2, s7, 1
	s_lshl_b64 s[24:25], s[2:3], 7
	s_add_i32 s2, s7, 2
	s_lshl_b64 s[46:47], s[2:3], 7
	s_add_u32 s48, s16, s46
	s_addc_u32 s49, s17, s47
	s_and_b64 s[22:23], s[20:21], exec
	s_cselect_b32 s23, s40, s49
	s_cselect_b32 s22, s41, s48
	s_add_u32 s46, s14, s46
	s_addc_u32 s47, s15, s47
	s_and_b64 s[20:21], s[20:21], exec
	s_cselect_b32 s21, s42, s47
	s_cselect_b32 s20, s43, s46
	s_add_i32 s46, 0, 0x10000
	v_add_u32_e32 v139, s46, v0
	s_add_i32 s47, 0, 0x14000
	ds_read_b128 v[140:143], v139
	ds_read_b128 v[144:147], v139 offset:1024
	ds_read_b128 v[148:151], v139 offset:2048
	ds_read_b128 v[152:155], v139 offset:3072
	v_add_u32_e32 v139, s47, v0
	ds_read_b128 v[156:159], v139
	ds_read_b128 v[160:163], v139 offset:1024
	ds_read_b128 v[164:167], v139 offset:2048
	ds_read_b128 v[168:171], v139 offset:3072
	s_add_u32 s24, s44, s24
	s_addc_u32 s25, s45, s25
	v_lshl_add_u64 v[200:201], s[24:25], 0, v[130:131]
	s_add_i32 m0, s28, 0xc000
	ds_read_b128 v[172:175], v138
	ds_read_b128 v[176:179], v138 offset:1024
	ds_read_b128 v[180:183], v138 offset:2048
	ds_read_b128 v[184:187], v138 offset:3072
	ds_read_b128 v[188:191], v138 offset:4096
	ds_read_b128 v[192:195], v138 offset:5120
	ds_read_b128 v[196:199], v138 offset:6144
	ds_read_b128 v[206:209], v138 offset:7168
	global_load_lds_dwordx4 v[200:201], off
	s_add_i32 m0, s28, 0xe000
	v_lshl_add_u64 v[200:201], s[24:25], 0, v[134:135]
	global_load_lds_dwordx4 v[200:201], off
	s_waitcnt vmcnt(8)
	s_waitcnt lgkmcnt(0)
	s_barrier
	s_setprio 1
	s_waitcnt lgkmcnt(0)
	v_mfma_f32_16x16x32_bf16 v[126:129], v[140:143], v[172:175], v[126:129]
	v_mfma_f32_16x16x32_bf16 v[122:125], v[148:151], v[172:175], v[122:125]
	v_mfma_f32_16x16x32_bf16 v[118:121], v[140:143], v[180:183], v[118:121]
	v_mfma_f32_16x16x32_bf16 v[110:113], v[148:151], v[180:183], v[110:113]
	v_mfma_f32_16x16x32_bf16 v[102:105], v[140:143], v[188:191], v[102:105]
	v_mfma_f32_16x16x32_bf16 v[94:97], v[148:151], v[188:191], v[94:97]
	v_mfma_f32_16x16x32_bf16 v[86:89], v[140:143], v[196:199], v[86:89]
	v_mfma_f32_16x16x32_bf16 v[78:81], v[148:151], v[196:199], v[78:81]
	v_mfma_f32_16x16x32_bf16 v[126:129], v[144:147], v[176:179], v[126:129]
	v_mfma_f32_16x16x32_bf16 v[122:125], v[152:155], v[176:179], v[122:125]
	v_mfma_f32_16x16x32_bf16 v[118:121], v[144:147], v[184:187], v[118:121]
	v_mfma_f32_16x16x32_bf16 v[110:113], v[152:155], v[184:187], v[110:113]
	v_mfma_f32_16x16x32_bf16 v[102:105], v[144:147], v[192:195], v[102:105]
	v_mfma_f32_16x16x32_bf16 v[94:97], v[152:155], v[192:195], v[94:97]
	v_mfma_f32_16x16x32_bf16 v[86:89], v[144:147], v[206:209], v[86:89]
	v_mfma_f32_16x16x32_bf16 v[78:81], v[152:155], v[206:209], v[78:81]
	s_setprio 0
	s_setprio 1
	v_mfma_f32_16x16x32_bf16 v[114:117], v[156:159], v[172:175], v[114:117]
	v_mfma_f32_16x16x32_bf16 v[106:109], v[164:167], v[172:175], v[106:109]
	v_mfma_f32_16x16x32_bf16 v[98:101], v[156:159], v[180:183], v[98:101]
	v_mfma_f32_16x16x32_bf16 v[90:93], v[164:167], v[180:183], v[90:93]
	v_mfma_f32_16x16x32_bf16 v[82:85], v[156:159], v[188:191], v[82:85]
	v_mfma_f32_16x16x32_bf16 v[74:77], v[164:167], v[188:191], v[74:77]
	v_mfma_f32_16x16x32_bf16 v[70:73], v[156:159], v[196:199], v[70:73]
	v_mfma_f32_16x16x32_bf16 v[66:69], v[164:167], v[196:199], v[66:69]
	v_mfma_f32_16x16x32_bf16 v[114:117], v[160:163], v[176:179], v[114:117]
	v_mfma_f32_16x16x32_bf16 v[106:109], v[168:171], v[176:179], v[106:109]
	v_mfma_f32_16x16x32_bf16 v[98:101], v[160:163], v[184:187], v[98:101]
	v_mfma_f32_16x16x32_bf16 v[90:93], v[168:171], v[184:187], v[90:93]
	v_mfma_f32_16x16x32_bf16 v[82:85], v[160:163], v[192:195], v[82:85]
	v_mfma_f32_16x16x32_bf16 v[74:77], v[168:171], v[192:195], v[74:77]
	v_mfma_f32_16x16x32_bf16 v[70:73], v[160:163], v[206:209], v[70:73]
	v_mfma_f32_16x16x32_bf16 v[66:69], v[168:171], v[206:209], v[66:69]
	s_setprio 0
	s_barrier
	s_add_i32 s24, s46, s27
	v_lshl_add_u64 v[200:201], s[20:21], 0, v[132:133]
	s_mov_b32 m0, s24
	ds_read_b128 v[172:175], v138 offset:16384
	ds_read_b128 v[176:179], v138 offset:17408
	ds_read_b128 v[180:183], v138 offset:18432
	ds_read_b128 v[184:187], v138 offset:19456
	ds_read_b128 v[188:191], v138 offset:20480
	ds_read_b128 v[192:195], v138 offset:21504
	ds_read_b128 v[196:199], v138 offset:22528
	ds_read_b128 v[206:209], v138 offset:23552
	global_load_lds_dwordx4 v[200:201], off
	s_add_i32 m0, s24, 0x2000
	s_add_u32 s24, s20, 0x40000
	v_lshl_add_u64 v[210:211], s[20:21], 0, v[136:137]
	s_addc_u32 s25, s21, 0
	s_add_i32 s46, s47, s27
	global_load_lds_dwordx4 v[210:211], off
	v_lshl_add_u64 v[212:213], s[24:25], 0, v[132:133]
	s_mov_b32 m0, s46
	v_lshl_add_u64 v[214:215], s[22:23], 0, v[134:135]
	global_load_lds_dwordx4 v[212:213], off
	s_add_i32 m0, s46, 0x2000
	v_lshl_add_u64 v[212:213], s[24:25], 0, v[136:137]
	global_load_lds_dwordx4 v[212:213], off
	s_mov_b32 m0, s28
	v_lshl_add_u64 v[212:213], s[22:23], 0, v[130:131]
	global_load_lds_dwordx4 v[212:213], off
	s_mov_b32 m0, s29
	s_nop 0
	global_load_lds_dwordx4 v[214:215], off
	s_waitcnt vmcnt(8)
	s_waitcnt lgkmcnt(0)
	s_barrier
; #define PG8_STAGE(bufoff, gbase, voff) do { _Pragma("unroll") for (int _i = 0; _i < 2; ++_i) \
;         __builtin_amdgcn_global_load_lds((const unsigned*)((const char*)(gbase) + (voff)[_i]), (PG8_LAS unsigned*)(lds + (bufoff) + ldsw + _i * 8192), 16, 0, 0); } while (0)
; #define PG8_LDA(dst, b, h) do { _Pragma("unroll") for (int m = 0; m < 4; ++m) _Pragma("unroll") for (int k = 0; k < 2; ++k) dst[m][k] = *(const PG8_LAS bf16x8*)(lds + PG8_SA(b, h) + aoff + m * 2048 + k * 1024); } while (0)
; #define PG8_LDB(dst, b, h) do { _Pragma("unroll") for (int n = 0; n < 2; ++n) _Pragma("unroll") for (int k = 0; k < 2; ++k) dst[n][k] = *(const PG8_LAS bf16x8*)(lds + PG8_SB(b, h) + boff + n * 2048 + k * 1024); } while (0)
; #define PG8_MMA(ai, bj, At, Bt) do { __builtin_amdgcn_s_setprio(1); _Pragma("unroll") for (int m = 0; m < 4; ++m) _Pragma("unroll") for (int n = 0; n < 2; ++n) _Pragma("unroll") for (int k = 0; k < 2; ++k) \
;         acc[ai][bj][m][n] = __builtin_amdgcn_mfma_f32_16x16x32_bf16(Bt[n][k], At[m][k], acc[ai][bj][m][n], 0, 0, 0); __builtin_amdgcn_s_setprio(0); } while (0)
; #define PG8_WAIT_V(n) asm volatile("s_waitcnt vmcnt(" #n ")" ::: "memory")
; #define PG8_WAIT_L(n) asm volatile("s_waitcnt lgkmcnt(" #n ")" ::: "memory")
; #define PG8_BAR __builtin_amdgcn_s_barrier()
; #define PG8_SCHED __builtin_amdgcn_sched_barrier(0)
; template <class Epi, class Sched, bool ALIGN_EPI = false, bool SP2 = false>
; __device__ __forceinline__ void gemm_phase(PG8_LAS unsigned char* lds, const Gemm g, const Sched& S, const Epi& E) {
;     ...
;             PG8_WAIT_V(8); PG8_WAIT_L(0); PG8_BAR; PG8_MMA(1, 0, At, B0); PG8_MMA(1, 1, At, B1); PG8_BAR; PG8_SCHED;
;             PG8_LDB(B0, 1, 0); PG8_LDB(B1, 1, 1); PG8_SCHED; PG8_LDA(At, 1, 0); PG8_STAGE(PG8_SA(0, 1), a2 + hstep, voffA);
;             PG8_WAIT_V(8); PG8_WAIT_L(0); PG8_BAR; PG8_MMA(0, 0, At, B0); PG8_MMA(0, 1, At, B1); PG8_BAR; PG8_SCHED;
	s_setprio 1
	s_waitcnt lgkmcnt(0)
	v_mfma_f32_16x16x32_bf16 v[62:65], v[140:143], v[172:175], v[62:65]
	v_mfma_f32_16x16x32_bf16 v[58:61], v[148:151], v[172:175], v[58:61]
	v_mfma_f32_16x16x32_bf16 v[54:57], v[140:143], v[180:183], v[54:57]
	v_mfma_f32_16x16x32_bf16 v[46:49], v[148:151], v[180:183], v[46:49]
	v_mfma_f32_16x16x32_bf16 v[38:41], v[140:143], v[188:191], v[38:41]
	v_mfma_f32_16x16x32_bf16 v[30:33], v[148:151], v[188:191], v[30:33]
	v_mfma_f32_16x16x32_bf16 v[22:25], v[140:143], v[196:199], v[22:25]
	v_mfma_f32_16x16x32_bf16 v[14:17], v[148:151], v[196:199], v[14:17]
	v_mfma_f32_16x16x32_bf16 v[62:65], v[144:147], v[176:179], v[62:65]
	v_mfma_f32_16x16x32_bf16 v[58:61], v[152:155], v[176:179], v[58:61]
	v_mfma_f32_16x16x32_bf16 v[54:57], v[144:147], v[184:187], v[54:57]
	v_mfma_f32_16x16x32_bf16 v[46:49], v[152:155], v[184:187], v[46:49]
	v_mfma_f32_16x16x32_bf16 v[38:41], v[144:147], v[192:195], v[38:41]
	v_mfma_f32_16x16x32_bf16 v[30:33], v[152:155], v[192:195], v[30:33]
	v_mfma_f32_16x16x32_bf16 v[22:25], v[144:147], v[206:209], v[22:25]
	v_mfma_f32_16x16x32_bf16 v[14:17], v[152:155], v[206:209], v[14:17]
	s_setprio 0
	s_setprio 1
	v_mfma_f32_16x16x32_bf16 v[50:53], v[156:159], v[172:175], v[50:53]
	v_mfma_f32_16x16x32_bf16 v[42:45], v[164:167], v[172:175], v[42:45]
	v_mfma_f32_16x16x32_bf16 v[34:37], v[156:159], v[180:183], v[34:37]
	v_mfma_f32_16x16x32_bf16 v[26:29], v[164:167], v[180:183], v[26:29]
	v_mfma_f32_16x16x32_bf16 v[18:21], v[156:159], v[188:191], v[18:21]
	v_mfma_f32_16x16x32_bf16 v[10:13], v[164:167], v[188:191], v[10:13]
	v_mfma_f32_16x16x32_bf16 v[6:9], v[156:159], v[196:199], v[6:9]
	v_mfma_f32_16x16x32_bf16 v[2:5], v[164:167], v[196:199], v[2:5]
	v_mfma_f32_16x16x32_bf16 v[50:53], v[160:163], v[176:179], v[50:53]
	v_mfma_f32_16x16x32_bf16 v[42:45], v[168:171], v[176:179], v[42:45]
	v_mfma_f32_16x16x32_bf16 v[34:37], v[160:163], v[184:187], v[34:37]
	v_mfma_f32_16x16x32_bf16 v[26:29], v[168:171], v[184:187], v[26:29]
	v_mfma_f32_16x16x32_bf16 v[18:21], v[160:163], v[192:195], v[18:21]
	v_mfma_f32_16x16x32_bf16 v[10:13], v[168:171], v[192:195], v[10:13]
	v_mfma_f32_16x16x32_bf16 v[6:9], v[160:163], v[206:209], v[6:9]
	v_mfma_f32_16x16x32_bf16 v[2:5], v[168:171], v[206:209], v[2:5]
	s_setprio 0
	s_barrier
	s_add_i32 s24, 0, 0x18000
	v_add_u32_e32 v139, s24, v0
	s_add_i32 s25, 0, 0x1c000
	ds_read_b128 v[140:143], v139
	ds_read_b128 v[144:147], v139 offset:1024
	ds_read_b128 v[148:151], v139 offset:2048
	ds_read_b128 v[152:155], v139 offset:3072
	v_add_u32_e32 v139, s25, v0
	ds_read_b128 v[156:159], v139
	ds_read_b128 v[160:163], v139 offset:1024
	ds_read_b128 v[164:167], v139 offset:2048
	ds_read_b128 v[168:171], v139 offset:3072
	s_add_u32 s22, s22, 0x40000
	s_addc_u32 s23, s23, 0
	s_mov_b32 m0, s31
	v_lshl_add_u64 v[216:217], s[22:23], 0, v[130:131]
	ds_read_b128 v[172:175], v138 offset:32768
	ds_read_b128 v[176:179], v138 offset:33792
	ds_read_b128 v[180:183], v138 offset:34816
	ds_read_b128 v[184:187], v138 offset:35840
	ds_read_b128 v[188:191], v138 offset:36864
	ds_read_b128 v[192:195], v138 offset:37888
	ds_read_b128 v[196:199], v138 offset:38912
	ds_read_b128 v[206:209], v138 offset:39936
	global_load_lds_dwordx4 v[216:217], off
	s_mov_b32 m0, s34
	v_lshl_add_u64 v[216:217], s[22:23], 0, v[134:135]
	global_load_lds_dwordx4 v[216:217], off
	s_waitcnt vmcnt(8)
	s_waitcnt lgkmcnt(0)
	s_barrier
	s_setprio 1
	s_waitcnt lgkmcnt(0)
	v_mfma_f32_16x16x32_bf16 v[126:129], v[140:143], v[172:175], v[126:129]
	v_mfma_f32_16x16x32_bf16 v[122:125], v[148:151], v[172:175], v[122:125]
	v_mfma_f32_16x16x32_bf16 v[118:121], v[140:143], v[180:183], v[118:121]
	v_mfma_f32_16x16x32_bf16 v[110:113], v[148:151], v[180:183], v[110:113]
	v_mfma_f32_16x16x32_bf16 v[102:105], v[140:143], v[188:191], v[102:105]
	v_mfma_f32_16x16x32_bf16 v[94:97], v[148:151], v[188:191], v[94:97]
	v_mfma_f32_16x16x32_bf16 v[86:89], v[140:143], v[196:199], v[86:89]
	v_mfma_f32_16x16x32_bf16 v[78:81], v[148:151], v[196:199], v[78:81]
	v_mfma_f32_16x16x32_bf16 v[126:129], v[144:147], v[176:179], v[126:129]
	v_mfma_f32_16x16x32_bf16 v[122:125], v[152:155], v[176:179], v[122:125]
	v_mfma_f32_16x16x32_bf16 v[118:121], v[144:147], v[184:187], v[118:121]
	v_mfma_f32_16x16x32_bf16 v[110:113], v[152:155], v[184:187], v[110:113]
	v_mfma_f32_16x16x32_bf16 v[102:105], v[144:147], v[192:195], v[102:105]
	v_mfma_f32_16x16x32_bf16 v[94:97], v[152:155], v[192:195], v[94:97]
	v_mfma_f32_16x16x32_bf16 v[86:89], v[144:147], v[206:209], v[86:89]
	v_mfma_f32_16x16x32_bf16 v[78:81], v[152:155], v[206:209], v[78:81]
	s_setprio 0
	s_setprio 1
	v_mfma_f32_16x16x32_bf16 v[114:117], v[156:159], v[172:175], v[114:117]
	v_mfma_f32_16x16x32_bf16 v[106:109], v[164:167], v[172:175], v[106:109]
	v_mfma_f32_16x16x32_bf16 v[98:101], v[156:159], v[180:183], v[98:101]
	v_mfma_f32_16x16x32_bf16 v[90:93], v[164:167], v[180:183], v[90:93]
	v_mfma_f32_16x16x32_bf16 v[82:85], v[156:159], v[188:191], v[82:85]
	v_mfma_f32_16x16x32_bf16 v[74:77], v[164:167], v[188:191], v[74:77]
	v_mfma_f32_16x16x32_bf16 v[70:73], v[156:159], v[196:199], v[70:73]
	v_mfma_f32_16x16x32_bf16 v[66:69], v[164:167], v[196:199], v[66:69]
	v_mfma_f32_16x16x32_bf16 v[114:117], v[160:163], v[176:179], v[114:117]
	v_mfma_f32_16x16x32_bf16 v[106:109], v[168:171], v[176:179], v[106:109]
	v_mfma_f32_16x16x32_bf16 v[98:101], v[160:163], v[184:187], v[98:101]
	v_mfma_f32_16x16x32_bf16 v[90:93], v[168:171], v[184:187], v[90:93]
	v_mfma_f32_16x16x32_bf16 v[82:85], v[160:163], v[192:195], v[82:85]
	v_mfma_f32_16x16x32_bf16 v[74:77], v[168:171], v[192:195], v[74:77]
	v_mfma_f32_16x16x32_bf16 v[70:73], v[160:163], v[206:209], v[70:73]
	v_mfma_f32_16x16x32_bf16 v[66:69], v[168:171], v[206:209], v[66:69]
	s_setprio 0
	s_barrier
; #define PG8_STAGE(bufoff, gbase, voff) do { _Pragma("unroll") for (int _i = 0; _i < 2; ++_i) \
;         __builtin_amdgcn_global_load_lds((const unsigned*)((const char*)(gbase) + (voff)[_i]), (PG8_LAS unsigned*)(lds + (bufoff) + ldsw + _i * 8192), 16, 0, 0); } while (0)
; #define PG8_LDA(dst, b, h) do { _Pragma("unroll") for (int m = 0; m < 4; ++m) _Pragma("unroll") for (int k = 0; k < 2; ++k) dst[m][k] = *(const PG8_LAS bf16x8*)(lds + PG8_SA(b, h) + aoff + m * 2048 + k * 1024); } while (0)
; #define PG8_MMA(ai, bj, At, Bt) do { __builtin_amdgcn_s_setprio(1); _Pragma("unroll") for (int m = 0; m < 4; ++m) _Pragma("unroll") for (int n = 0; n < 2; ++n) _Pragma("unroll") for (int k = 0; k < 2; ++k) \
;         acc[ai][bj][m][n] = __builtin_amdgcn_mfma_f32_16x16x32_bf16(Bt[n][k], At[m][k], acc[ai][bj][m][n], 0, 0, 0); __builtin_amdgcn_s_setprio(0); } while (0)
; #define PG8_WAIT_V(n) asm volatile("s_waitcnt vmcnt(" #n ")" ::: "memory")
; #define PG8_WAIT_L(n) asm volatile("s_waitcnt lgkmcnt(" #n ")" ::: "memory")
; #define PG8_BAR __builtin_amdgcn_s_barrier()
; #define PG8_SCHED __builtin_amdgcn_sched_barrier(0)
; template <class Epi, class Sched, bool ALIGN_EPI = false, bool SP2 = false>
; __device__ __forceinline__ void gemm_phase(PG8_LAS unsigned char* lds, const Gemm g, const Sched& S, const Epi& E) {
;     ...
;         for (int t = 0; t < nt; t += 2) {
;     ...
;             PG8_LDA(At, 1, 1); PG8_STAGE(PG8_SB(1, 0), b3, voffB); PG8_STAGE(PG8_SB(1, 1), b3 + hstep, voffB); PG8_STAGE(PG8_SA(1, 0), a3, voffA);
;             PG8_WAIT_V(8); PG8_WAIT_L(0); PG8_BAR; PG8_MMA(1, 0, At, B0); PG8_MMA(1, 1, At, B1); PG8_BAR; PG8_SCHED;
	s_mov_b64 s[46:47], 0x80
	s_add_i32 s22, s24, s27
	v_lshl_add_u64 v[200:201], v[200:201], 0, s[46:47]
	s_mov_b32 m0, s22
	ds_read_b128 v[172:175], v138 offset:49152
	ds_read_b128 v[176:179], v138 offset:50176
	ds_read_b128 v[180:183], v138 offset:51200
	ds_read_b128 v[184:187], v138 offset:52224
	ds_read_b128 v[188:191], v138 offset:53248
	ds_read_b128 v[192:195], v138 offset:54272
	ds_read_b128 v[196:199], v138 offset:55296
	ds_read_b128 v[206:209], v138 offset:56320
	global_load_lds_dwordx4 v[200:201], off
	s_add_i32 m0, s22, 0x2000
	s_add_u32 s20, s20, 0x40080
	v_lshl_add_u64 v[200:201], v[210:211], 0, s[46:47]
	s_addc_u32 s21, s21, 0
	s_add_i32 s22, s25, s27
	global_load_lds_dwordx4 v[200:201], off
	s_mov_b32 m0, s22
	v_lshl_add_u64 v[200:201], s[20:21], 0, v[132:133]
	global_load_lds_dwordx4 v[200:201], off
	s_add_i32 m0, s22, 0x2000
	v_lshl_add_u64 v[200:201], s[20:21], 0, v[136:137]
	global_load_lds_dwordx4 v[200:201], off
	s_mov_b32 m0, s35
	v_lshl_add_u64 v[200:201], v[212:213], 0, s[46:47]
	global_load_lds_dwordx4 v[200:201], off
	s_mov_b32 m0, s36
	v_lshl_add_u64 v[200:201], v[214:215], 0, s[46:47]
	global_load_lds_dwordx4 v[200:201], off
	s_waitcnt vmcnt(8)
	s_waitcnt lgkmcnt(0)
	s_barrier
	s_setprio 1
	s_waitcnt lgkmcnt(0)
	v_mfma_f32_16x16x32_bf16 v[62:65], v[140:143], v[172:175], v[62:65]
	v_mfma_f32_16x16x32_bf16 v[58:61], v[148:151], v[172:175], v[58:61]
	v_mfma_f32_16x16x32_bf16 v[54:57], v[140:143], v[180:183], v[54:57]
	v_mfma_f32_16x16x32_bf16 v[46:49], v[148:151], v[180:183], v[46:49]
	v_mfma_f32_16x16x32_bf16 v[38:41], v[140:143], v[188:191], v[38:41]
	v_mfma_f32_16x16x32_bf16 v[30:33], v[148:151], v[188:191], v[30:33]
	v_mfma_f32_16x16x32_bf16 v[22:25], v[140:143], v[196:199], v[22:25]
	v_mfma_f32_16x16x32_bf16 v[14:17], v[148:151], v[196:199], v[14:17]
	v_mfma_f32_16x16x32_bf16 v[62:65], v[144:147], v[176:179], v[62:65]
	v_mfma_f32_16x16x32_bf16 v[58:61], v[152:155], v[176:179], v[58:61]
	v_mfma_f32_16x16x32_bf16 v[54:57], v[144:147], v[184:187], v[54:57]
	v_mfma_f32_16x16x32_bf16 v[46:49], v[152:155], v[184:187], v[46:49]
	v_mfma_f32_16x16x32_bf16 v[38:41], v[144:147], v[192:195], v[38:41]
	v_mfma_f32_16x16x32_bf16 v[30:33], v[152:155], v[192:195], v[30:33]
	v_mfma_f32_16x16x32_bf16 v[22:25], v[144:147], v[206:209], v[22:25]
	v_mfma_f32_16x16x32_bf16 v[14:17], v[152:155], v[206:209], v[14:17]
	s_setprio 0
	s_setprio 1
	v_mfma_f32_16x16x32_bf16 v[50:53], v[156:159], v[172:175], v[50:53]
	v_mfma_f32_16x16x32_bf16 v[42:45], v[164:167], v[172:175], v[42:45]
	v_mfma_f32_16x16x32_bf16 v[34:37], v[156:159], v[180:183], v[34:37]
	v_mfma_f32_16x16x32_bf16 v[26:29], v[164:167], v[180:183], v[26:29]
	v_mfma_f32_16x16x32_bf16 v[18:21], v[156:159], v[188:191], v[18:21]
	v_mfma_f32_16x16x32_bf16 v[10:13], v[164:167], v[188:191], v[10:13]
	v_mfma_f32_16x16x32_bf16 v[6:9], v[156:159], v[196:199], v[6:9]
	v_mfma_f32_16x16x32_bf16 v[2:5], v[164:167], v[196:199], v[2:5]
	v_mfma_f32_16x16x32_bf16 v[50:53], v[160:163], v[176:179], v[50:53]
	v_mfma_f32_16x16x32_bf16 v[42:45], v[168:171], v[176:179], v[42:45]
	v_mfma_f32_16x16x32_bf16 v[34:37], v[160:163], v[184:187], v[34:37]
	v_mfma_f32_16x16x32_bf16 v[26:29], v[168:171], v[184:187], v[26:29]
	v_mfma_f32_16x16x32_bf16 v[18:21], v[160:163], v[192:195], v[18:21]
	v_mfma_f32_16x16x32_bf16 v[10:13], v[168:171], v[192:195], v[10:13]
	v_mfma_f32_16x16x32_bf16 v[6:9], v[160:163], v[206:209], v[6:9]
	v_mfma_f32_16x16x32_bf16 v[2:5], v[168:171], v[206:209], v[2:5]
	s_setprio 0
	s_barrier
	s_cmp_gt_u32 s7, 13
	s_mov_b32 s7, s2
	s_cbranch_scc1 .LBB0_1250
